# peeled first K-iteration with SrcC=0 (no accumulator zeroing) in the four GEMM loops + final-phase fast path
# speedup vs baseline: 1.0111x; 1.0111x over previous
.LBB0_109:
	v_lshrrev_b32_e32 v9, 1, v99
	v_and_b32_e32 v9, 24, v9
	v_and_b32_e32 v8, 15, v99
	v_lshlrev_b32_e32 v10, 1, v9
	v_lshl_or_b32 v150, s25, 6, v8
	v_lshl_or_b32 v10, v8, 6, v10
	v_lshlrev_b32_e32 v8, 2, v8
	s_lshl_b32 s21, s21, 5
	s_lshl_b32 s25, s25, 13
	v_and_b32_e32 v11, 32, v8
	s_and_b32 s21, s21, 0x60
	s_add_i32 m0, s46, 0x18000
	v_lshl_add_u64 v[2:3], v[2:3], 0, s[12:13]
	v_bitop3_b32 v12, v10, s25, v11 bitop3:0xde
	s_lshl_b32 s25, s21, 7
	s_waitcnt vmcnt(2)
	s_barrier
	global_load_lds_dwordx4 v[2:3], off
	v_lshl_add_u64 v[2:3], v[4:5], 0, s[12:13]
	s_add_i32 m0, s46, 0x1a000
	s_add_i32 s50, s46, 0x8000
	s_add_i32 s51, s46, 0xa000
	global_load_lds_dwordx4 v[2:3], off
	v_lshl_add_u64 v[0:1], v[0:1], 0, s[12:13]
	s_mov_b32 m0, s50
	s_add_u32 s26, s0, 0x80080
	global_load_lds_dwordx4 v[0:1], off
	v_lshl_add_u64 v[0:1], v[6:7], 0, s[12:13]
	s_mov_b32 m0, s51
	s_addc_u32 s27, s1, 0
	global_load_lds_dwordx4 v[0:1], off
	s_add_i32 m0, s46, 0x1c000
	v_lshl_add_u64 v[0:1], s[26:27], 0, v[204:205]
	global_load_lds_dwordx4 v[0:1], off
	v_lshl_add_u64 v[0:1], s[26:27], 0, v[128:129]
	s_add_i32 m0, s46, 0x1e000
	s_cmpk_lt_u32 s20, 0x100
	global_load_lds_dwordx4 v[0:1], off
	v_lshlrev_b32_e32 v0, 15, v101
	v_and_b32_e32 v0, 0xffff0000, v0
	v_lshl_add_u32 v0, v100, 12, v0
	v_and_b32_e32 v1, 1, v101
	v_lshl_or_b32 v0, v1, 6, v0
	v_lshl_add_u32 v134, v102, 1, v0
	v_lshlrev_b32_e32 v0, 15, v96
	v_and_b32_e32 v0, 0xffff0000, v0
	s_cselect_b64 s[26:27], -1, 0
	s_and_b32 s20, s20, 0xffffff00
	v_lshl_add_u32 v0, v97, 12, v0
	v_and_b32_e32 v1, 1, v96
	s_waitcnt vmcnt(6)
	s_add_i32 s20, s20, 0
	v_lshl_or_b32 v0, v1, 6, v0
	s_add_i32 s20, s20, 0x20000
	v_lshl_add_u32 v136, v98, 1, v0
	v_bitop3_b32 v151, v10, s25, v11 bitop3:0xde
	v_add_u32_e32 v152, s20, v8
	v_or_b32_e32 v153, s21, v9
	v_mov_b32_e32 v135, v205
	v_mov_b32_e32 v137, v205
	s_mov_b32 s53, 0
	v_add_u32_e32 v154, 0, v12
	v_readlane_b32 s52, v253, 19
	s_mov_b32 s54, s28
	s_mov_b32 s56, 0
	s_barrier
	s_branch .LBB0_111
.LBB0_110:
	s_mov_b32 s52, s28
	s_mov_b32 s54, s36
	s_mov_b32 s53, s55
	s_mov_b64 s[4:5], s[40:41]
	s_mov_b32 s56, s57
	s_andn2_b64 vcc, exec, s[60:61]
	s_mov_b64 s[0:1], s[38:39]
	s_cbranch_vccz .LBB0_121

.LBB0_113:
	s_add_u32 s20, s0, 0x100
	s_addc_u32 s21, s1, 0
	s_ashr_i32 s37, s36, 31
	s_lshl_b64 s[38:39], s[36:37], 20
	s_add_u32 s40, s16, s38
	s_addc_u32 s41, s17, s39
	s_and_b64 s[38:39], s[62:63], exec
	s_cselect_b32 s25, s41, s5
	s_cselect_b32 s37, s40, s4
	s_ashr_i32 s29, s28, 31
	s_lshl_b64 s[38:39], s[28:29], 20
	s_add_u32 s38, s3, s38
	s_addc_u32 s39, s22, s39
	s_and_b64 s[42:43], s[62:63], exec
	s_cselect_b32 s29, s39, s1
	s_cselect_b32 s64, s38, s0
	s_add_u32 s0, s4, 0x80080
	s_addc_u32 s1, s5, 0
	v_lshl_add_u64 v[138:139], s[0:1], 0, v[134:135]
	v_lshl_add_u64 v[140:141], s[0:1], 0, v[136:137]
	s_mov_b32 s65, -2
	s_mov_b64 s[0:1], 0
	s_add_u32 s42, s4, s0
	s_addc_u32 s43, s5, s1
	s_add_u32 s42, s42, 0x100
	s_addc_u32 s43, s43, 0
	s_add_u32 s66, s20, s0
	s_addc_u32 s67, s21, s1
	s_add_i32 s70, 0, 0x10000
	s_cmpk_eq_i32 s0, 0xf00
	s_cselect_b32 s45, s25, s43
	s_cselect_b32 s44, s37, s42
	v_add_u32_e32 v155, s70, v151
	s_cselect_b32 s43, s29, s67
	s_cselect_b32 s42, s64, s66
	s_add_i32 s71, 0, 0x14000
	ds_read_b128 v[142:145], v155
	ds_read_b128 v[146:149], v155 offset:1024
	ds_read_b128 v[156:159], v155 offset:2048
	ds_read_b128 v[160:163], v155 offset:3072
	v_add_u32_e32 v155, s71, v151
	ds_read_b128 v[164:167], v155
	ds_read_b128 v[168:171], v155 offset:1024
	ds_read_b128 v[172:175], v155 offset:2048
	ds_read_b128 v[176:179], v155 offset:3072
	v_lshl_add_u64 v[222:223], v[138:139], 0, s[0:1]
	s_add_i32 m0, s46, 0xc000
	ds_read_b128 v[180:183], v154
	ds_read_b128 v[184:187], v154 offset:1024
	ds_read_b128 v[188:191], v154 offset:2048
	ds_read_b128 v[192:195], v154 offset:3072
	ds_read_b128 v[196:199], v154 offset:4096
	ds_read_b128 v[210:213], v154 offset:5120
	ds_read_b128 v[214:217], v154 offset:6144
	ds_read_b128 v[218:221], v154 offset:7168
	global_load_lds_dwordx4 v[222:223], off
	v_lshl_add_u64 v[222:223], v[140:141], 0, s[0:1]
	s_add_i32 m0, s46, 0xe000
	s_nop 0
	global_load_lds_dwordx4 v[222:223], off
	s_waitcnt vmcnt(8)
	s_waitcnt lgkmcnt(0)
	s_barrier
	s_setprio 1
	s_waitcnt lgkmcnt(0)
	v_mfma_f32_16x16x32_bf16 v[124:127], v[142:145], v[180:183], 0
	v_mfma_f32_16x16x32_bf16 v[120:123], v[156:159], v[180:183], 0
	v_mfma_f32_16x16x32_bf16 v[116:119], v[142:145], v[188:191], 0
	v_mfma_f32_16x16x32_bf16 v[112:115], v[156:159], v[188:191], 0
	v_mfma_f32_16x16x32_bf16 v[108:111], v[142:145], v[196:199], 0
	v_mfma_f32_16x16x32_bf16 v[104:107], v[156:159], v[196:199], 0
	v_mfma_f32_16x16x32_bf16 v[100:103], v[142:145], v[214:217], 0
	v_mfma_f32_16x16x32_bf16 v[96:99], v[156:159], v[214:217], 0
	v_mfma_f32_16x16x32_bf16 v[124:127], v[146:149], v[184:187], v[124:127]
	v_mfma_f32_16x16x32_bf16 v[120:123], v[160:163], v[184:187], v[120:123]
	v_mfma_f32_16x16x32_bf16 v[116:119], v[146:149], v[192:195], v[116:119]
	v_mfma_f32_16x16x32_bf16 v[112:115], v[160:163], v[192:195], v[112:115]
	v_mfma_f32_16x16x32_bf16 v[108:111], v[146:149], v[210:213], v[108:111]
	v_mfma_f32_16x16x32_bf16 v[104:107], v[160:163], v[210:213], v[104:107]
	v_mfma_f32_16x16x32_bf16 v[100:103], v[146:149], v[218:221], v[100:103]
	v_mfma_f32_16x16x32_bf16 v[96:99], v[160:163], v[218:221], v[96:99]
	s_setprio 0
	s_setprio 1
	v_mfma_f32_16x16x32_bf16 v[92:95], v[164:167], v[180:183], 0
	v_mfma_f32_16x16x32_bf16 v[88:91], v[172:175], v[180:183], 0
	v_mfma_f32_16x16x32_bf16 v[84:87], v[164:167], v[188:191], 0
	v_mfma_f32_16x16x32_bf16 v[80:83], v[172:175], v[188:191], 0
	v_mfma_f32_16x16x32_bf16 v[76:79], v[164:167], v[196:199], 0
	v_mfma_f32_16x16x32_bf16 v[72:75], v[172:175], v[196:199], 0
	v_mfma_f32_16x16x32_bf16 v[68:71], v[164:167], v[214:217], 0
	v_mfma_f32_16x16x32_bf16 v[64:67], v[172:175], v[214:217], 0
	v_mfma_f32_16x16x32_bf16 v[92:95], v[168:171], v[184:187], v[92:95]
	v_mfma_f32_16x16x32_bf16 v[88:91], v[176:179], v[184:187], v[88:91]
	v_mfma_f32_16x16x32_bf16 v[84:87], v[168:171], v[192:195], v[84:87]
	v_mfma_f32_16x16x32_bf16 v[80:83], v[176:179], v[192:195], v[80:83]
	v_mfma_f32_16x16x32_bf16 v[76:79], v[168:171], v[210:213], v[76:79]
	v_mfma_f32_16x16x32_bf16 v[72:75], v[176:179], v[210:213], v[72:75]
	v_mfma_f32_16x16x32_bf16 v[68:71], v[168:171], v[218:221], v[68:71]
	v_mfma_f32_16x16x32_bf16 v[64:67], v[176:179], v[218:221], v[64:67]
	s_setprio 0
	s_barrier
	s_add_i32 s66, s70, s2
	v_lshl_add_u64 v[222:223], s[42:43], 0, v[204:205]
	s_mov_b32 m0, s66
	ds_read_b128 v[180:183], v154 offset:16384
	ds_read_b128 v[184:187], v154 offset:17408
	ds_read_b128 v[188:191], v154 offset:18432
	ds_read_b128 v[192:195], v154 offset:19456
	ds_read_b128 v[196:199], v154 offset:20480
	ds_read_b128 v[210:213], v154 offset:21504
	ds_read_b128 v[214:217], v154 offset:22528
	ds_read_b128 v[218:221], v154 offset:23552
	global_load_lds_dwordx4 v[222:223], off
	s_add_i32 m0, s66, 0x2000
	s_add_u32 s66, s42, 0x80000
	v_lshl_add_u64 v[224:225], s[42:43], 0, v[128:129]
	s_addc_u32 s67, s43, 0
	s_add_i32 s70, s71, s2
	global_load_lds_dwordx4 v[224:225], off
	v_lshl_add_u64 v[226:227], s[66:67], 0, v[204:205]
	s_mov_b32 m0, s70
	v_lshl_add_u64 v[228:229], s[44:45], 0, v[130:131]
	global_load_lds_dwordx4 v[226:227], off
	v_lshl_add_u64 v[226:227], s[66:67], 0, v[128:129]
	s_add_i32 m0, s70, 0x2000
	s_nop 0
	global_load_lds_dwordx4 v[226:227], off
	v_lshl_add_u64 v[226:227], s[44:45], 0, v[132:133]
	s_mov_b32 m0, s46
	s_nop 0
	global_load_lds_dwordx4 v[226:227], off
	s_mov_b32 m0, s47
	s_nop 0
	global_load_lds_dwordx4 v[228:229], off
	s_waitcnt vmcnt(8)
	s_waitcnt lgkmcnt(0)
	s_barrier
	s_setprio 1
	s_waitcnt lgkmcnt(0)
	v_mfma_f32_16x16x32_bf16 v[60:63], v[142:145], v[180:183], 0
	v_mfma_f32_16x16x32_bf16 v[56:59], v[156:159], v[180:183], 0
	v_mfma_f32_16x16x32_bf16 v[52:55], v[142:145], v[188:191], 0
	v_mfma_f32_16x16x32_bf16 v[48:51], v[156:159], v[188:191], 0
	v_mfma_f32_16x16x32_bf16 v[44:47], v[142:145], v[196:199], 0
	v_mfma_f32_16x16x32_bf16 v[40:43], v[156:159], v[196:199], 0
	v_mfma_f32_16x16x32_bf16 v[36:39], v[142:145], v[214:217], 0
	v_mfma_f32_16x16x32_bf16 v[32:35], v[156:159], v[214:217], 0
	v_mfma_f32_16x16x32_bf16 v[60:63], v[146:149], v[184:187], v[60:63]
	v_mfma_f32_16x16x32_bf16 v[56:59], v[160:163], v[184:187], v[56:59]
	v_mfma_f32_16x16x32_bf16 v[52:55], v[146:149], v[192:195], v[52:55]
	v_mfma_f32_16x16x32_bf16 v[48:51], v[160:163], v[192:195], v[48:51]
	v_mfma_f32_16x16x32_bf16 v[44:47], v[146:149], v[210:213], v[44:47]
	v_mfma_f32_16x16x32_bf16 v[40:43], v[160:163], v[210:213], v[40:43]
	v_mfma_f32_16x16x32_bf16 v[36:39], v[146:149], v[218:221], v[36:39]
	v_mfma_f32_16x16x32_bf16 v[32:35], v[160:163], v[218:221], v[32:35]
	s_setprio 0
	s_setprio 1
	v_mfma_f32_16x16x32_bf16 v[28:31], v[164:167], v[180:183], 0
	v_mfma_f32_16x16x32_bf16 v[24:27], v[172:175], v[180:183], 0
	v_mfma_f32_16x16x32_bf16 v[20:23], v[164:167], v[188:191], 0
	v_mfma_f32_16x16x32_bf16 v[16:19], v[172:175], v[188:191], 0
	v_mfma_f32_16x16x32_bf16 v[12:15], v[164:167], v[196:199], 0
	v_mfma_f32_16x16x32_bf16 v[8:11], v[172:175], v[196:199], 0
	v_mfma_f32_16x16x32_bf16 v[4:7], v[164:167], v[214:217], 0
	v_mfma_f32_16x16x32_bf16 v[0:3], v[172:175], v[214:217], 0
	v_mfma_f32_16x16x32_bf16 v[28:31], v[168:171], v[184:187], v[28:31]
	v_mfma_f32_16x16x32_bf16 v[24:27], v[176:179], v[184:187], v[24:27]
	v_mfma_f32_16x16x32_bf16 v[20:23], v[168:171], v[192:195], v[20:23]
	v_mfma_f32_16x16x32_bf16 v[16:19], v[176:179], v[192:195], v[16:19]
	v_mfma_f32_16x16x32_bf16 v[12:15], v[168:171], v[210:213], v[12:15]
	v_mfma_f32_16x16x32_bf16 v[8:11], v[176:179], v[210:213], v[8:11]
	v_mfma_f32_16x16x32_bf16 v[4:7], v[168:171], v[218:221], v[4:7]
	v_mfma_f32_16x16x32_bf16 v[0:3], v[176:179], v[218:221], v[0:3]
	s_setprio 0
	s_barrier
	s_add_i32 s66, 0, 0x18000
	v_add_u32_e32 v155, s66, v151
	s_add_i32 s67, 0, 0x1c000
	ds_read_b128 v[142:145], v155
	ds_read_b128 v[146:149], v155 offset:1024
	ds_read_b128 v[156:159], v155 offset:2048
	ds_read_b128 v[160:163], v155 offset:3072
	v_add_u32_e32 v155, s67, v151
	ds_read_b128 v[164:167], v155
	ds_read_b128 v[168:171], v155 offset:1024
	ds_read_b128 v[172:175], v155 offset:2048
	ds_read_b128 v[176:179], v155 offset:3072
	s_add_u32 s44, s44, 0x80000
	s_addc_u32 s45, s45, 0
	s_mov_b32 m0, s48
	v_lshl_add_u64 v[230:231], s[44:45], 0, v[132:133]
	ds_read_b128 v[180:183], v154 offset:32768
	ds_read_b128 v[184:187], v154 offset:33792
	ds_read_b128 v[188:191], v154 offset:34816
	ds_read_b128 v[192:195], v154 offset:35840
	ds_read_b128 v[196:199], v154 offset:36864
	ds_read_b128 v[210:213], v154 offset:37888
	ds_read_b128 v[214:217], v154 offset:38912
	ds_read_b128 v[218:221], v154 offset:39936
	global_load_lds_dwordx4 v[230:231], off
	v_lshl_add_u64 v[230:231], s[44:45], 0, v[130:131]
	s_mov_b32 m0, s49
	s_nop 0
	global_load_lds_dwordx4 v[230:231], off
	s_waitcnt vmcnt(8)
	s_waitcnt lgkmcnt(0)
	s_barrier
	s_setprio 1
	s_waitcnt lgkmcnt(0)
	v_mfma_f32_16x16x32_bf16 v[124:127], v[142:145], v[180:183], v[124:127]
	v_mfma_f32_16x16x32_bf16 v[120:123], v[156:159], v[180:183], v[120:123]
	v_mfma_f32_16x16x32_bf16 v[116:119], v[142:145], v[188:191], v[116:119]
	v_mfma_f32_16x16x32_bf16 v[112:115], v[156:159], v[188:191], v[112:115]
	v_mfma_f32_16x16x32_bf16 v[108:111], v[142:145], v[196:199], v[108:111]
	v_mfma_f32_16x16x32_bf16 v[104:107], v[156:159], v[196:199], v[104:107]
	v_mfma_f32_16x16x32_bf16 v[100:103], v[142:145], v[214:217], v[100:103]
	v_mfma_f32_16x16x32_bf16 v[96:99], v[156:159], v[214:217], v[96:99]
	v_mfma_f32_16x16x32_bf16 v[124:127], v[146:149], v[184:187], v[124:127]
	v_mfma_f32_16x16x32_bf16 v[120:123], v[160:163], v[184:187], v[120:123]
	v_mfma_f32_16x16x32_bf16 v[116:119], v[146:149], v[192:195], v[116:119]
	v_mfma_f32_16x16x32_bf16 v[112:115], v[160:163], v[192:195], v[112:115]
	v_mfma_f32_16x16x32_bf16 v[108:111], v[146:149], v[210:213], v[108:111]
	v_mfma_f32_16x16x32_bf16 v[104:107], v[160:163], v[210:213], v[104:107]
	v_mfma_f32_16x16x32_bf16 v[100:103], v[146:149], v[218:221], v[100:103]
	v_mfma_f32_16x16x32_bf16 v[96:99], v[160:163], v[218:221], v[96:99]
	s_setprio 0
	s_setprio 1
	v_mfma_f32_16x16x32_bf16 v[92:95], v[164:167], v[180:183], v[92:95]
	v_mfma_f32_16x16x32_bf16 v[88:91], v[172:175], v[180:183], v[88:91]
	v_mfma_f32_16x16x32_bf16 v[84:87], v[164:167], v[188:191], v[84:87]
	v_mfma_f32_16x16x32_bf16 v[80:83], v[172:175], v[188:191], v[80:83]
	v_mfma_f32_16x16x32_bf16 v[76:79], v[164:167], v[196:199], v[76:79]
	v_mfma_f32_16x16x32_bf16 v[72:75], v[172:175], v[196:199], v[72:75]
	v_mfma_f32_16x16x32_bf16 v[68:71], v[164:167], v[214:217], v[68:71]
	v_mfma_f32_16x16x32_bf16 v[64:67], v[172:175], v[214:217], v[64:67]
	v_mfma_f32_16x16x32_bf16 v[92:95], v[168:171], v[184:187], v[92:95]
	v_mfma_f32_16x16x32_bf16 v[88:91], v[176:179], v[184:187], v[88:91]
	v_mfma_f32_16x16x32_bf16 v[84:87], v[168:171], v[192:195], v[84:87]
	v_mfma_f32_16x16x32_bf16 v[80:83], v[176:179], v[192:195], v[80:83]
	v_mfma_f32_16x16x32_bf16 v[76:79], v[168:171], v[210:213], v[76:79]
	v_mfma_f32_16x16x32_bf16 v[72:75], v[176:179], v[210:213], v[72:75]
	v_mfma_f32_16x16x32_bf16 v[68:71], v[168:171], v[218:221], v[68:71]
	v_mfma_f32_16x16x32_bf16 v[64:67], v[176:179], v[218:221], v[64:67]
	s_setprio 0
	s_barrier
	s_add_i32 s44, s66, s2
	v_lshl_add_u64 v[222:223], v[222:223], 0, s[12:13]
	s_mov_b32 m0, s44
	ds_read_b128 v[180:183], v154 offset:49152
	ds_read_b128 v[184:187], v154 offset:50176
	ds_read_b128 v[188:191], v154 offset:51200
	ds_read_b128 v[192:195], v154 offset:52224
	ds_read_b128 v[196:199], v154 offset:53248
	ds_read_b128 v[210:213], v154 offset:54272
	ds_read_b128 v[214:217], v154 offset:55296
	ds_read_b128 v[218:221], v154 offset:56320
	global_load_lds_dwordx4 v[222:223], off
	s_add_i32 m0, s44, 0x2000
	s_add_u32 s42, s42, 0x80080
	v_lshl_add_u64 v[222:223], v[224:225], 0, s[12:13]
	s_addc_u32 s43, s43, 0
	s_add_i32 s44, s67, s2
	global_load_lds_dwordx4 v[222:223], off
	v_lshl_add_u64 v[222:223], s[42:43], 0, v[204:205]
	s_mov_b32 m0, s44
	s_nop 0
	global_load_lds_dwordx4 v[222:223], off
	v_lshl_add_u64 v[222:223], s[42:43], 0, v[128:129]
	s_add_i32 m0, s44, 0x2000
	s_nop 0
	global_load_lds_dwordx4 v[222:223], off
	v_lshl_add_u64 v[222:223], v[226:227], 0, s[12:13]
	s_mov_b32 m0, s50
	s_nop 0
	global_load_lds_dwordx4 v[222:223], off
	v_lshl_add_u64 v[222:223], v[228:229], 0, s[12:13]
	s_mov_b32 m0, s51
	s_nop 0
	global_load_lds_dwordx4 v[222:223], off
	s_waitcnt vmcnt(8)
	s_waitcnt lgkmcnt(0)
	s_barrier
	s_setprio 1
	s_waitcnt lgkmcnt(0)
	v_mfma_f32_16x16x32_bf16 v[60:63], v[142:145], v[180:183], v[60:63]
	v_mfma_f32_16x16x32_bf16 v[56:59], v[156:159], v[180:183], v[56:59]
	v_mfma_f32_16x16x32_bf16 v[52:55], v[142:145], v[188:191], v[52:55]
	v_mfma_f32_16x16x32_bf16 v[48:51], v[156:159], v[188:191], v[48:51]
	v_mfma_f32_16x16x32_bf16 v[44:47], v[142:145], v[196:199], v[44:47]
	v_mfma_f32_16x16x32_bf16 v[40:43], v[156:159], v[196:199], v[40:43]
	v_mfma_f32_16x16x32_bf16 v[36:39], v[142:145], v[214:217], v[36:39]
	v_mfma_f32_16x16x32_bf16 v[32:35], v[156:159], v[214:217], v[32:35]
	v_mfma_f32_16x16x32_bf16 v[60:63], v[146:149], v[184:187], v[60:63]
	v_mfma_f32_16x16x32_bf16 v[56:59], v[160:163], v[184:187], v[56:59]
	v_mfma_f32_16x16x32_bf16 v[52:55], v[146:149], v[192:195], v[52:55]
	v_mfma_f32_16x16x32_bf16 v[48:51], v[160:163], v[192:195], v[48:51]
	v_mfma_f32_16x16x32_bf16 v[44:47], v[146:149], v[210:213], v[44:47]
	v_mfma_f32_16x16x32_bf16 v[40:43], v[160:163], v[210:213], v[40:43]
	v_mfma_f32_16x16x32_bf16 v[36:39], v[146:149], v[218:221], v[36:39]
	v_mfma_f32_16x16x32_bf16 v[32:35], v[160:163], v[218:221], v[32:35]
	s_setprio 0
	s_setprio 1
	v_mfma_f32_16x16x32_bf16 v[28:31], v[164:167], v[180:183], v[28:31]
	v_mfma_f32_16x16x32_bf16 v[24:27], v[172:175], v[180:183], v[24:27]
	v_mfma_f32_16x16x32_bf16 v[20:23], v[164:167], v[188:191], v[20:23]
	v_mfma_f32_16x16x32_bf16 v[16:19], v[172:175], v[188:191], v[16:19]
	v_mfma_f32_16x16x32_bf16 v[12:15], v[164:167], v[196:199], v[12:15]
	v_mfma_f32_16x16x32_bf16 v[8:11], v[172:175], v[196:199], v[8:11]
	v_mfma_f32_16x16x32_bf16 v[4:7], v[164:167], v[214:217], v[4:7]
	v_mfma_f32_16x16x32_bf16 v[0:3], v[172:175], v[214:217], v[0:3]
	v_mfma_f32_16x16x32_bf16 v[28:31], v[168:171], v[184:187], v[28:31]
	v_mfma_f32_16x16x32_bf16 v[24:27], v[176:179], v[184:187], v[24:27]
	v_mfma_f32_16x16x32_bf16 v[20:23], v[168:171], v[192:195], v[20:23]
	v_mfma_f32_16x16x32_bf16 v[16:19], v[176:179], v[192:195], v[16:19]
	v_mfma_f32_16x16x32_bf16 v[12:15], v[168:171], v[210:213], v[12:15]
	v_mfma_f32_16x16x32_bf16 v[8:11], v[176:179], v[210:213], v[8:11]
	v_mfma_f32_16x16x32_bf16 v[4:7], v[168:171], v[218:221], v[4:7]
	v_mfma_f32_16x16x32_bf16 v[0:3], v[176:179], v[218:221], v[0:3]
	s_setprio 0
	s_barrier
	s_add_i32 s65, s65, 2
	s_add_u32 s0, s0, 0x100
	s_addc_u32 s1, s1, 0
	s_cmp_gt_u32 s65, 29
	s_cbranch_scc1 .Lpeel_exit_114
.LBB0_114:
	s_add_u32 s42, s4, s0
	s_addc_u32 s43, s5, s1
	s_add_u32 s42, s42, 0x100
	s_addc_u32 s43, s43, 0
	s_add_u32 s66, s20, s0
	s_addc_u32 s67, s21, s1
	s_add_i32 s70, 0, 0x10000
	s_cmpk_eq_i32 s0, 0xf00
	s_cselect_b32 s45, s25, s43
	s_cselect_b32 s44, s37, s42
	v_add_u32_e32 v155, s70, v151
	s_cselect_b32 s43, s29, s67
	s_cselect_b32 s42, s64, s66
	s_add_i32 s71, 0, 0x14000
	ds_read_b128 v[142:145], v155
	ds_read_b128 v[146:149], v155 offset:1024
	ds_read_b128 v[156:159], v155 offset:2048
	ds_read_b128 v[160:163], v155 offset:3072
	v_add_u32_e32 v155, s71, v151
	ds_read_b128 v[164:167], v155
	ds_read_b128 v[168:171], v155 offset:1024
	ds_read_b128 v[172:175], v155 offset:2048
	ds_read_b128 v[176:179], v155 offset:3072
	v_lshl_add_u64 v[222:223], v[138:139], 0, s[0:1]
	s_add_i32 m0, s46, 0xc000
	ds_read_b128 v[180:183], v154
	ds_read_b128 v[184:187], v154 offset:1024
	ds_read_b128 v[188:191], v154 offset:2048
	ds_read_b128 v[192:195], v154 offset:3072
	ds_read_b128 v[196:199], v154 offset:4096
	ds_read_b128 v[210:213], v154 offset:5120
	ds_read_b128 v[214:217], v154 offset:6144
	ds_read_b128 v[218:221], v154 offset:7168
	global_load_lds_dwordx4 v[222:223], off
	v_lshl_add_u64 v[222:223], v[140:141], 0, s[0:1]
	s_add_i32 m0, s46, 0xe000
	s_nop 0
	global_load_lds_dwordx4 v[222:223], off
	s_waitcnt vmcnt(8)
	s_waitcnt lgkmcnt(0)
	s_barrier
	s_setprio 1
	s_waitcnt lgkmcnt(0)
	v_mfma_f32_16x16x32_bf16 v[124:127], v[142:145], v[180:183], v[124:127]
	v_mfma_f32_16x16x32_bf16 v[120:123], v[156:159], v[180:183], v[120:123]
	v_mfma_f32_16x16x32_bf16 v[116:119], v[142:145], v[188:191], v[116:119]
	v_mfma_f32_16x16x32_bf16 v[112:115], v[156:159], v[188:191], v[112:115]
	v_mfma_f32_16x16x32_bf16 v[108:111], v[142:145], v[196:199], v[108:111]
	v_mfma_f32_16x16x32_bf16 v[104:107], v[156:159], v[196:199], v[104:107]
	v_mfma_f32_16x16x32_bf16 v[100:103], v[142:145], v[214:217], v[100:103]
	v_mfma_f32_16x16x32_bf16 v[96:99], v[156:159], v[214:217], v[96:99]
	v_mfma_f32_16x16x32_bf16 v[124:127], v[146:149], v[184:187], v[124:127]
	v_mfma_f32_16x16x32_bf16 v[120:123], v[160:163], v[184:187], v[120:123]
	v_mfma_f32_16x16x32_bf16 v[116:119], v[146:149], v[192:195], v[116:119]
	v_mfma_f32_16x16x32_bf16 v[112:115], v[160:163], v[192:195], v[112:115]
	v_mfma_f32_16x16x32_bf16 v[108:111], v[146:149], v[210:213], v[108:111]
	v_mfma_f32_16x16x32_bf16 v[104:107], v[160:163], v[210:213], v[104:107]
	v_mfma_f32_16x16x32_bf16 v[100:103], v[146:149], v[218:221], v[100:103]
	v_mfma_f32_16x16x32_bf16 v[96:99], v[160:163], v[218:221], v[96:99]
	s_setprio 0
	s_setprio 1
	v_mfma_f32_16x16x32_bf16 v[92:95], v[164:167], v[180:183], v[92:95]
	v_mfma_f32_16x16x32_bf16 v[88:91], v[172:175], v[180:183], v[88:91]
	v_mfma_f32_16x16x32_bf16 v[84:87], v[164:167], v[188:191], v[84:87]
	v_mfma_f32_16x16x32_bf16 v[80:83], v[172:175], v[188:191], v[80:83]
	v_mfma_f32_16x16x32_bf16 v[76:79], v[164:167], v[196:199], v[76:79]
	v_mfma_f32_16x16x32_bf16 v[72:75], v[172:175], v[196:199], v[72:75]
	v_mfma_f32_16x16x32_bf16 v[68:71], v[164:167], v[214:217], v[68:71]
	v_mfma_f32_16x16x32_bf16 v[64:67], v[172:175], v[214:217], v[64:67]
	v_mfma_f32_16x16x32_bf16 v[92:95], v[168:171], v[184:187], v[92:95]
	v_mfma_f32_16x16x32_bf16 v[88:91], v[176:179], v[184:187], v[88:91]
	v_mfma_f32_16x16x32_bf16 v[84:87], v[168:171], v[192:195], v[84:87]
	v_mfma_f32_16x16x32_bf16 v[80:83], v[176:179], v[192:195], v[80:83]
	v_mfma_f32_16x16x32_bf16 v[76:79], v[168:171], v[210:213], v[76:79]
	v_mfma_f32_16x16x32_bf16 v[72:75], v[176:179], v[210:213], v[72:75]
	v_mfma_f32_16x16x32_bf16 v[68:71], v[168:171], v[218:221], v[68:71]
	v_mfma_f32_16x16x32_bf16 v[64:67], v[176:179], v[218:221], v[64:67]
	s_setprio 0
	s_barrier
	s_add_i32 s66, s70, s2
	v_lshl_add_u64 v[222:223], s[42:43], 0, v[204:205]
	s_mov_b32 m0, s66
	ds_read_b128 v[180:183], v154 offset:16384
	ds_read_b128 v[184:187], v154 offset:17408
	ds_read_b128 v[188:191], v154 offset:18432
	ds_read_b128 v[192:195], v154 offset:19456
	ds_read_b128 v[196:199], v154 offset:20480
	ds_read_b128 v[210:213], v154 offset:21504
	ds_read_b128 v[214:217], v154 offset:22528
	ds_read_b128 v[218:221], v154 offset:23552
	global_load_lds_dwordx4 v[222:223], off
	s_add_i32 m0, s66, 0x2000
	s_add_u32 s66, s42, 0x80000
	v_lshl_add_u64 v[224:225], s[42:43], 0, v[128:129]
	s_addc_u32 s67, s43, 0
	s_add_i32 s70, s71, s2
	global_load_lds_dwordx4 v[224:225], off
	v_lshl_add_u64 v[226:227], s[66:67], 0, v[204:205]
	s_mov_b32 m0, s70
	v_lshl_add_u64 v[228:229], s[44:45], 0, v[130:131]
	global_load_lds_dwordx4 v[226:227], off
	v_lshl_add_u64 v[226:227], s[66:67], 0, v[128:129]
	s_add_i32 m0, s70, 0x2000
	s_nop 0
	global_load_lds_dwordx4 v[226:227], off
	v_lshl_add_u64 v[226:227], s[44:45], 0, v[132:133]
	s_mov_b32 m0, s46
	s_nop 0
	global_load_lds_dwordx4 v[226:227], off
	s_mov_b32 m0, s47
	s_nop 0
	global_load_lds_dwordx4 v[228:229], off
	s_waitcnt vmcnt(8)
	s_waitcnt lgkmcnt(0)
	s_barrier
	s_setprio 1
	s_waitcnt lgkmcnt(0)
	v_mfma_f32_16x16x32_bf16 v[60:63], v[142:145], v[180:183], v[60:63]
	v_mfma_f32_16x16x32_bf16 v[56:59], v[156:159], v[180:183], v[56:59]
	v_mfma_f32_16x16x32_bf16 v[52:55], v[142:145], v[188:191], v[52:55]
	v_mfma_f32_16x16x32_bf16 v[48:51], v[156:159], v[188:191], v[48:51]
	v_mfma_f32_16x16x32_bf16 v[44:47], v[142:145], v[196:199], v[44:47]
	v_mfma_f32_16x16x32_bf16 v[40:43], v[156:159], v[196:199], v[40:43]
	v_mfma_f32_16x16x32_bf16 v[36:39], v[142:145], v[214:217], v[36:39]
	v_mfma_f32_16x16x32_bf16 v[32:35], v[156:159], v[214:217], v[32:35]
	v_mfma_f32_16x16x32_bf16 v[60:63], v[146:149], v[184:187], v[60:63]
	v_mfma_f32_16x16x32_bf16 v[56:59], v[160:163], v[184:187], v[56:59]
	v_mfma_f32_16x16x32_bf16 v[52:55], v[146:149], v[192:195], v[52:55]
	v_mfma_f32_16x16x32_bf16 v[48:51], v[160:163], v[192:195], v[48:51]
	v_mfma_f32_16x16x32_bf16 v[44:47], v[146:149], v[210:213], v[44:47]
	v_mfma_f32_16x16x32_bf16 v[40:43], v[160:163], v[210:213], v[40:43]
	v_mfma_f32_16x16x32_bf16 v[36:39], v[146:149], v[218:221], v[36:39]
	v_mfma_f32_16x16x32_bf16 v[32:35], v[160:163], v[218:221], v[32:35]
	s_setprio 0
	s_setprio 1
	v_mfma_f32_16x16x32_bf16 v[28:31], v[164:167], v[180:183], v[28:31]
	v_mfma_f32_16x16x32_bf16 v[24:27], v[172:175], v[180:183], v[24:27]
	v_mfma_f32_16x16x32_bf16 v[20:23], v[164:167], v[188:191], v[20:23]
	v_mfma_f32_16x16x32_bf16 v[16:19], v[172:175], v[188:191], v[16:19]
	v_mfma_f32_16x16x32_bf16 v[12:15], v[164:167], v[196:199], v[12:15]
	v_mfma_f32_16x16x32_bf16 v[8:11], v[172:175], v[196:199], v[8:11]
	v_mfma_f32_16x16x32_bf16 v[4:7], v[164:167], v[214:217], v[4:7]
	v_mfma_f32_16x16x32_bf16 v[0:3], v[172:175], v[214:217], v[0:3]
	v_mfma_f32_16x16x32_bf16 v[28:31], v[168:171], v[184:187], v[28:31]
	v_mfma_f32_16x16x32_bf16 v[24:27], v[176:179], v[184:187], v[24:27]
	v_mfma_f32_16x16x32_bf16 v[20:23], v[168:171], v[192:195], v[20:23]
	v_mfma_f32_16x16x32_bf16 v[16:19], v[176:179], v[192:195], v[16:19]
	v_mfma_f32_16x16x32_bf16 v[12:15], v[168:171], v[210:213], v[12:15]
	v_mfma_f32_16x16x32_bf16 v[8:11], v[176:179], v[210:213], v[8:11]
	v_mfma_f32_16x16x32_bf16 v[4:7], v[168:171], v[218:221], v[4:7]
	v_mfma_f32_16x16x32_bf16 v[0:3], v[176:179], v[218:221], v[0:3]
	s_setprio 0
	s_barrier
	s_add_i32 s66, 0, 0x18000
	v_add_u32_e32 v155, s66, v151
	s_add_i32 s67, 0, 0x1c000
	ds_read_b128 v[142:145], v155
	ds_read_b128 v[146:149], v155 offset:1024
	ds_read_b128 v[156:159], v155 offset:2048
	ds_read_b128 v[160:163], v155 offset:3072
	v_add_u32_e32 v155, s67, v151
	ds_read_b128 v[164:167], v155
	ds_read_b128 v[168:171], v155 offset:1024
	ds_read_b128 v[172:175], v155 offset:2048
	ds_read_b128 v[176:179], v155 offset:3072
	s_add_u32 s44, s44, 0x80000
	s_addc_u32 s45, s45, 0
	s_mov_b32 m0, s48
	v_lshl_add_u64 v[230:231], s[44:45], 0, v[132:133]
	ds_read_b128 v[180:183], v154 offset:32768
	ds_read_b128 v[184:187], v154 offset:33792
	ds_read_b128 v[188:191], v154 offset:34816
	ds_read_b128 v[192:195], v154 offset:35840
	ds_read_b128 v[196:199], v154 offset:36864
	ds_read_b128 v[210:213], v154 offset:37888
	ds_read_b128 v[214:217], v154 offset:38912
	ds_read_b128 v[218:221], v154 offset:39936
	global_load_lds_dwordx4 v[230:231], off
	v_lshl_add_u64 v[230:231], s[44:45], 0, v[130:131]
	s_mov_b32 m0, s49
	s_nop 0
	global_load_lds_dwordx4 v[230:231], off
	s_waitcnt vmcnt(8)
	s_waitcnt lgkmcnt(0)
	s_barrier
	s_setprio 1
	s_waitcnt lgkmcnt(0)
	v_mfma_f32_16x16x32_bf16 v[124:127], v[142:145], v[180:183], v[124:127]
	v_mfma_f32_16x16x32_bf16 v[120:123], v[156:159], v[180:183], v[120:123]
	v_mfma_f32_16x16x32_bf16 v[116:119], v[142:145], v[188:191], v[116:119]
	v_mfma_f32_16x16x32_bf16 v[112:115], v[156:159], v[188:191], v[112:115]
	v_mfma_f32_16x16x32_bf16 v[108:111], v[142:145], v[196:199], v[108:111]
	v_mfma_f32_16x16x32_bf16 v[104:107], v[156:159], v[196:199], v[104:107]
	v_mfma_f32_16x16x32_bf16 v[100:103], v[142:145], v[214:217], v[100:103]
	v_mfma_f32_16x16x32_bf16 v[96:99], v[156:159], v[214:217], v[96:99]
	v_mfma_f32_16x16x32_bf16 v[124:127], v[146:149], v[184:187], v[124:127]
	v_mfma_f32_16x16x32_bf16 v[120:123], v[160:163], v[184:187], v[120:123]
	v_mfma_f32_16x16x32_bf16 v[116:119], v[146:149], v[192:195], v[116:119]
	v_mfma_f32_16x16x32_bf16 v[112:115], v[160:163], v[192:195], v[112:115]
	v_mfma_f32_16x16x32_bf16 v[108:111], v[146:149], v[210:213], v[108:111]
	v_mfma_f32_16x16x32_bf16 v[104:107], v[160:163], v[210:213], v[104:107]
	v_mfma_f32_16x16x32_bf16 v[100:103], v[146:149], v[218:221], v[100:103]
	v_mfma_f32_16x16x32_bf16 v[96:99], v[160:163], v[218:221], v[96:99]
	s_setprio 0
	s_setprio 1
	v_mfma_f32_16x16x32_bf16 v[92:95], v[164:167], v[180:183], v[92:95]
	v_mfma_f32_16x16x32_bf16 v[88:91], v[172:175], v[180:183], v[88:91]
	v_mfma_f32_16x16x32_bf16 v[84:87], v[164:167], v[188:191], v[84:87]
	v_mfma_f32_16x16x32_bf16 v[80:83], v[172:175], v[188:191], v[80:83]
	v_mfma_f32_16x16x32_bf16 v[76:79], v[164:167], v[196:199], v[76:79]
	v_mfma_f32_16x16x32_bf16 v[72:75], v[172:175], v[196:199], v[72:75]
	v_mfma_f32_16x16x32_bf16 v[68:71], v[164:167], v[214:217], v[68:71]
	v_mfma_f32_16x16x32_bf16 v[64:67], v[172:175], v[214:217], v[64:67]
	v_mfma_f32_16x16x32_bf16 v[92:95], v[168:171], v[184:187], v[92:95]
	v_mfma_f32_16x16x32_bf16 v[88:91], v[176:179], v[184:187], v[88:91]
	v_mfma_f32_16x16x32_bf16 v[84:87], v[168:171], v[192:195], v[84:87]
	v_mfma_f32_16x16x32_bf16 v[80:83], v[176:179], v[192:195], v[80:83]
	v_mfma_f32_16x16x32_bf16 v[76:79], v[168:171], v[210:213], v[76:79]
	v_mfma_f32_16x16x32_bf16 v[72:75], v[176:179], v[210:213], v[72:75]
	v_mfma_f32_16x16x32_bf16 v[68:71], v[168:171], v[218:221], v[68:71]
	v_mfma_f32_16x16x32_bf16 v[64:67], v[176:179], v[218:221], v[64:67]
	s_setprio 0
	s_barrier
	s_add_i32 s44, s66, s2
	v_lshl_add_u64 v[222:223], v[222:223], 0, s[12:13]
	s_mov_b32 m0, s44
	ds_read_b128 v[180:183], v154 offset:49152
	ds_read_b128 v[184:187], v154 offset:50176
	ds_read_b128 v[188:191], v154 offset:51200
	ds_read_b128 v[192:195], v154 offset:52224
	ds_read_b128 v[196:199], v154 offset:53248
	ds_read_b128 v[210:213], v154 offset:54272
	ds_read_b128 v[214:217], v154 offset:55296
	ds_read_b128 v[218:221], v154 offset:56320
	global_load_lds_dwordx4 v[222:223], off
	s_add_i32 m0, s44, 0x2000
	s_add_u32 s42, s42, 0x80080
	v_lshl_add_u64 v[222:223], v[224:225], 0, s[12:13]
	s_addc_u32 s43, s43, 0
	s_add_i32 s44, s67, s2
	global_load_lds_dwordx4 v[222:223], off
	v_lshl_add_u64 v[222:223], s[42:43], 0, v[204:205]
	s_mov_b32 m0, s44
	s_nop 0
	global_load_lds_dwordx4 v[222:223], off
	v_lshl_add_u64 v[222:223], s[42:43], 0, v[128:129]
	s_add_i32 m0, s44, 0x2000
	s_nop 0
	global_load_lds_dwordx4 v[222:223], off
	v_lshl_add_u64 v[222:223], v[226:227], 0, s[12:13]
	s_mov_b32 m0, s50
	s_nop 0
	global_load_lds_dwordx4 v[222:223], off
	v_lshl_add_u64 v[222:223], v[228:229], 0, s[12:13]
	s_mov_b32 m0, s51
	s_nop 0
	global_load_lds_dwordx4 v[222:223], off
	s_waitcnt vmcnt(8)
	s_waitcnt lgkmcnt(0)
	s_barrier
	s_setprio 1
	s_waitcnt lgkmcnt(0)
	v_mfma_f32_16x16x32_bf16 v[60:63], v[142:145], v[180:183], v[60:63]
	v_mfma_f32_16x16x32_bf16 v[56:59], v[156:159], v[180:183], v[56:59]
	v_mfma_f32_16x16x32_bf16 v[52:55], v[142:145], v[188:191], v[52:55]
	v_mfma_f32_16x16x32_bf16 v[48:51], v[156:159], v[188:191], v[48:51]
	v_mfma_f32_16x16x32_bf16 v[44:47], v[142:145], v[196:199], v[44:47]
	v_mfma_f32_16x16x32_bf16 v[40:43], v[156:159], v[196:199], v[40:43]
	v_mfma_f32_16x16x32_bf16 v[36:39], v[142:145], v[214:217], v[36:39]
	v_mfma_f32_16x16x32_bf16 v[32:35], v[156:159], v[214:217], v[32:35]
	v_mfma_f32_16x16x32_bf16 v[60:63], v[146:149], v[184:187], v[60:63]
	v_mfma_f32_16x16x32_bf16 v[56:59], v[160:163], v[184:187], v[56:59]
	v_mfma_f32_16x16x32_bf16 v[52:55], v[146:149], v[192:195], v[52:55]
	v_mfma_f32_16x16x32_bf16 v[48:51], v[160:163], v[192:195], v[48:51]
	v_mfma_f32_16x16x32_bf16 v[44:47], v[146:149], v[210:213], v[44:47]
	v_mfma_f32_16x16x32_bf16 v[40:43], v[160:163], v[210:213], v[40:43]
	v_mfma_f32_16x16x32_bf16 v[36:39], v[146:149], v[218:221], v[36:39]
	v_mfma_f32_16x16x32_bf16 v[32:35], v[160:163], v[218:221], v[32:35]
	s_setprio 0
	s_setprio 1
	v_mfma_f32_16x16x32_bf16 v[28:31], v[164:167], v[180:183], v[28:31]
	v_mfma_f32_16x16x32_bf16 v[24:27], v[172:175], v[180:183], v[24:27]
	v_mfma_f32_16x16x32_bf16 v[20:23], v[164:167], v[188:191], v[20:23]
	v_mfma_f32_16x16x32_bf16 v[16:19], v[172:175], v[188:191], v[16:19]
	v_mfma_f32_16x16x32_bf16 v[12:15], v[164:167], v[196:199], v[12:15]
	v_mfma_f32_16x16x32_bf16 v[8:11], v[172:175], v[196:199], v[8:11]
	v_mfma_f32_16x16x32_bf16 v[4:7], v[164:167], v[214:217], v[4:7]
	v_mfma_f32_16x16x32_bf16 v[0:3], v[172:175], v[214:217], v[0:3]
	v_mfma_f32_16x16x32_bf16 v[28:31], v[168:171], v[184:187], v[28:31]
	v_mfma_f32_16x16x32_bf16 v[24:27], v[176:179], v[184:187], v[24:27]
	v_mfma_f32_16x16x32_bf16 v[20:23], v[168:171], v[192:195], v[20:23]
	v_mfma_f32_16x16x32_bf16 v[16:19], v[176:179], v[192:195], v[16:19]
	v_mfma_f32_16x16x32_bf16 v[12:15], v[168:171], v[210:213], v[12:15]
	v_mfma_f32_16x16x32_bf16 v[8:11], v[176:179], v[210:213], v[8:11]
	v_mfma_f32_16x16x32_bf16 v[4:7], v[168:171], v[218:221], v[4:7]
	v_mfma_f32_16x16x32_bf16 v[0:3], v[176:179], v[218:221], v[0:3]
	s_setprio 0
	s_barrier
	s_add_i32 s65, s65, 2
	s_add_u32 s0, s0, 0x100
	s_addc_u32 s1, s1, 0
	s_cmp_gt_u32 s65, 29
	s_cbranch_scc0 .LBB0_114
.Lpeel_exit_114:
	s_and_b64 vcc, exec, s[26:27]
	s_cbranch_vccz .LBB0_117
	s_barrier

.LBB0_182:
	s_add_u32 s0, s0, 0x80
	s_addc_u32 s1, s1, 0
	s_add_u32 s21, s36, 0x100
	s_addc_u32 s22, s37, 0
	s_mov_b32 s4, 0
	s_add_i32 s25, s4, 2
	s_add_u32 s28, s0, 0x80
	s_addc_u32 s5, s1, 0
	s_add_i32 s36, 0, 0x10000
	s_cmp_eq_u32 s63, s4
	s_cselect_b32 s5, s49, s5
	s_cselect_b32 s4, s48, s28
	s_cselect_b32 s29, s51, s22
	s_cselect_b32 s28, s50, s21
	s_add_i32 s37, 0, 0x14000
	v_add_u32_e32 v100, s36, v249
	v_add_u32_e32 v156, s37, v249
	ds_read_b128 v[88:91], v100
	ds_read_b128 v[92:95], v100 offset:1024
	ds_read_b128 v[96:99], v100 offset:2048
	ds_read_b128 v[100:103], v100 offset:3072
	s_waitcnt lgkmcnt(0)
	ds_read_b128 v[144:147], v156
	ds_read_b128 v[148:151], v156 offset:1024
	ds_read_b128 v[152:155], v156 offset:2048
	ds_read_b128 v[156:159], v156 offset:3072
	v_lshl_add_u64 v[192:193], s[0:1], 0, v[216:217]
	s_add_i32 m0, s3, 0xc000
	ds_read_b128 v[160:163], v251
	ds_read_b128 v[164:167], v251 offset:1024
	ds_read_b128 v[168:171], v251 offset:2048
	ds_read_b128 v[172:175], v251 offset:3072
	ds_read_b128 v[176:179], v251 offset:4096
	ds_read_b128 v[180:183], v251 offset:5120
	ds_read_b128 v[184:187], v251 offset:6144
	ds_read_b128 v[188:191], v251 offset:7168
	global_load_lds_dwordx4 v[192:193], off
	v_lshl_add_u64 v[192:193], s[0:1], 0, v[218:219]
	s_add_i32 m0, s3, 0xe000
	s_nop 0
	global_load_lds_dwordx4 v[192:193], off
	s_waitcnt vmcnt(8)
	s_waitcnt lgkmcnt(0)
	s_barrier
	s_setprio 1
	s_waitcnt lgkmcnt(0)
	v_mfma_f32_16x16x32_bf16 v[140:143], v[88:91], v[160:163], 0
	v_mfma_f32_16x16x32_bf16 v[136:139], v[96:99], v[160:163], 0
	v_mfma_f32_16x16x32_bf16 v[124:127], v[88:91], v[168:171], 0
	v_mfma_f32_16x16x32_bf16 v[120:123], v[96:99], v[168:171], 0
	v_mfma_f32_16x16x32_bf16 v[108:111], v[88:91], v[176:179], 0
	v_mfma_f32_16x16x32_bf16 v[104:107], v[96:99], v[176:179], 0
	v_mfma_f32_16x16x32_bf16 v[76:79], v[88:91], v[184:187], 0
	v_mfma_f32_16x16x32_bf16 v[72:75], v[96:99], v[184:187], 0
	v_mfma_f32_16x16x32_bf16 v[140:143], v[92:95], v[164:167], v[140:143]
	v_mfma_f32_16x16x32_bf16 v[136:139], v[100:103], v[164:167], v[136:139]
	v_mfma_f32_16x16x32_bf16 v[124:127], v[92:95], v[172:175], v[124:127]
	v_mfma_f32_16x16x32_bf16 v[120:123], v[100:103], v[172:175], v[120:123]
	v_mfma_f32_16x16x32_bf16 v[108:111], v[92:95], v[180:183], v[108:111]
	v_mfma_f32_16x16x32_bf16 v[104:107], v[100:103], v[180:183], v[104:107]
	v_mfma_f32_16x16x32_bf16 v[76:79], v[92:95], v[188:191], v[76:79]
	v_mfma_f32_16x16x32_bf16 v[72:75], v[100:103], v[188:191], v[72:75]
	s_setprio 0
	s_setprio 1
	v_mfma_f32_16x16x32_bf16 v[132:135], v[144:147], v[160:163], 0
	v_mfma_f32_16x16x32_bf16 v[128:131], v[152:155], v[160:163], 0
	v_mfma_f32_16x16x32_bf16 v[116:119], v[144:147], v[168:171], 0
	v_mfma_f32_16x16x32_bf16 v[112:115], v[152:155], v[168:171], 0
	v_mfma_f32_16x16x32_bf16 v[84:87], v[144:147], v[176:179], 0
	v_mfma_f32_16x16x32_bf16 v[80:83], v[152:155], v[176:179], 0
	v_mfma_f32_16x16x32_bf16 v[68:71], v[144:147], v[184:187], 0
	v_mfma_f32_16x16x32_bf16 v[64:67], v[152:155], v[184:187], 0
	v_mfma_f32_16x16x32_bf16 v[132:135], v[148:151], v[164:167], v[132:135]
	v_mfma_f32_16x16x32_bf16 v[128:131], v[156:159], v[164:167], v[128:131]
	v_mfma_f32_16x16x32_bf16 v[116:119], v[148:151], v[172:175], v[116:119]
	v_mfma_f32_16x16x32_bf16 v[112:115], v[156:159], v[172:175], v[112:115]
	v_mfma_f32_16x16x32_bf16 v[84:87], v[148:151], v[180:183], v[84:87]
	v_mfma_f32_16x16x32_bf16 v[80:83], v[156:159], v[180:183], v[80:83]
	v_mfma_f32_16x16x32_bf16 v[68:71], v[148:151], v[188:191], v[68:71]
	v_mfma_f32_16x16x32_bf16 v[64:67], v[156:159], v[188:191], v[64:67]
	s_setprio 0
	s_barrier
	s_add_i32 s36, s36, s2
	v_lshl_add_u64 v[192:193], s[28:29], 0, v[204:205]
	s_mov_b32 m0, s36
	ds_read_b128 v[160:163], v251 offset:16384
	ds_read_b128 v[164:167], v251 offset:17408
	ds_read_b128 v[168:171], v251 offset:18432
	ds_read_b128 v[172:175], v251 offset:19456
	ds_read_b128 v[176:179], v251 offset:20480
	ds_read_b128 v[180:183], v251 offset:21504
	ds_read_b128 v[184:187], v251 offset:22528
	ds_read_b128 v[188:191], v251 offset:23552
	global_load_lds_dwordx4 v[192:193], off
	s_add_i32 m0, s36, 0x2000
	v_lshl_add_u64 v[194:195], s[28:29], 0, v[210:211]
	s_add_u32 s28, s28, s10
	s_addc_u32 s29, s29, 0
	s_add_i32 s36, s37, s2
	global_load_lds_dwordx4 v[194:195], off
	v_lshl_add_u64 v[196:197], s[28:29], 0, v[204:205]
	s_mov_b32 m0, s36
	v_lshl_add_u64 v[198:199], s[28:29], 0, v[210:211]
	global_load_lds_dwordx4 v[196:197], off
	s_add_i32 m0, s36, 0x2000
	v_lshl_add_u64 v[220:221], s[4:5], 0, v[214:215]
	global_load_lds_dwordx4 v[198:199], off
	s_mov_b32 m0, s3
	v_lshl_add_u64 v[222:223], s[4:5], 0, v[212:213]
	global_load_lds_dwordx4 v[220:221], off
	s_mov_b32 m0, s52
	s_nop 0
	global_load_lds_dwordx4 v[222:223], off
	s_waitcnt vmcnt(8)
	s_waitcnt lgkmcnt(0)
	s_barrier
	s_setprio 1
	s_waitcnt lgkmcnt(0)
	v_mfma_f32_16x16x32_bf16 v[60:63], v[88:91], v[160:163], 0
	v_mfma_f32_16x16x32_bf16 v[56:59], v[96:99], v[160:163], 0
	v_mfma_f32_16x16x32_bf16 v[44:47], v[88:91], v[168:171], 0
	v_mfma_f32_16x16x32_bf16 v[40:43], v[96:99], v[168:171], 0
	v_mfma_f32_16x16x32_bf16 v[28:31], v[88:91], v[176:179], 0
	v_mfma_f32_16x16x32_bf16 v[24:27], v[96:99], v[176:179], 0
	v_mfma_f32_16x16x32_bf16 v[12:15], v[88:91], v[184:187], 0
	v_mfma_f32_16x16x32_bf16 v[8:11], v[96:99], v[184:187], 0
	v_mfma_f32_16x16x32_bf16 v[60:63], v[92:95], v[164:167], v[60:63]
	v_mfma_f32_16x16x32_bf16 v[56:59], v[100:103], v[164:167], v[56:59]
	v_mfma_f32_16x16x32_bf16 v[44:47], v[92:95], v[172:175], v[44:47]
	v_mfma_f32_16x16x32_bf16 v[40:43], v[100:103], v[172:175], v[40:43]
	v_mfma_f32_16x16x32_bf16 v[28:31], v[92:95], v[180:183], v[28:31]
	v_mfma_f32_16x16x32_bf16 v[24:27], v[100:103], v[180:183], v[24:27]
	v_mfma_f32_16x16x32_bf16 v[12:15], v[92:95], v[188:191], v[12:15]
	v_mfma_f32_16x16x32_bf16 v[8:11], v[100:103], v[188:191], v[8:11]
	s_setprio 0
	s_setprio 1
	v_mfma_f32_16x16x32_bf16 v[52:55], v[144:147], v[160:163], 0
	v_mfma_f32_16x16x32_bf16 v[48:51], v[152:155], v[160:163], 0
	v_mfma_f32_16x16x32_bf16 v[36:39], v[144:147], v[168:171], 0
	v_mfma_f32_16x16x32_bf16 v[32:35], v[152:155], v[168:171], 0
	v_mfma_f32_16x16x32_bf16 v[20:23], v[144:147], v[176:179], 0
	v_mfma_f32_16x16x32_bf16 v[16:19], v[152:155], v[176:179], 0
	v_mfma_f32_16x16x32_bf16 v[4:7], v[144:147], v[184:187], 0
	v_mfma_f32_16x16x32_bf16 v[0:3], v[152:155], v[184:187], 0
	v_mfma_f32_16x16x32_bf16 v[52:55], v[148:151], v[164:167], v[52:55]
	v_mfma_f32_16x16x32_bf16 v[48:51], v[156:159], v[164:167], v[48:51]
	v_mfma_f32_16x16x32_bf16 v[36:39], v[148:151], v[172:175], v[36:39]
	v_mfma_f32_16x16x32_bf16 v[32:35], v[156:159], v[172:175], v[32:35]
	v_mfma_f32_16x16x32_bf16 v[20:23], v[148:151], v[180:183], v[20:23]
	v_mfma_f32_16x16x32_bf16 v[16:19], v[156:159], v[180:183], v[16:19]
	v_mfma_f32_16x16x32_bf16 v[4:7], v[148:151], v[188:191], v[4:7]
	v_mfma_f32_16x16x32_bf16 v[0:3], v[156:159], v[188:191], v[0:3]
	s_setprio 0
	s_barrier
	s_add_i32 s28, 0, 0x18000
	s_add_i32 s29, 0, 0x1c000
	v_add_u32_e32 v100, s28, v249
	v_add_u32_e32 v156, s29, v249
	ds_read_b128 v[88:91], v100
	ds_read_b128 v[92:95], v100 offset:1024
	ds_read_b128 v[96:99], v100 offset:2048
	ds_read_b128 v[100:103], v100 offset:3072
	ds_read_b128 v[144:147], v156
	ds_read_b128 v[148:151], v156 offset:1024
	ds_read_b128 v[152:155], v156 offset:2048
	ds_read_b128 v[156:159], v156 offset:3072
	s_add_u32 s4, s4, s10
	s_addc_u32 s5, s5, 0
	s_mov_b32 m0, s53
	v_lshl_add_u64 v[224:225], s[4:5], 0, v[214:215]
	ds_read_b128 v[160:163], v251 offset:32768
	ds_read_b128 v[164:167], v251 offset:33792
	ds_read_b128 v[168:171], v251 offset:34816
	ds_read_b128 v[172:175], v251 offset:35840
	ds_read_b128 v[176:179], v251 offset:36864
	ds_read_b128 v[180:183], v251 offset:37888
	ds_read_b128 v[184:187], v251 offset:38912
	ds_read_b128 v[188:191], v251 offset:39936
	global_load_lds_dwordx4 v[224:225], off
	v_lshl_add_u64 v[224:225], s[4:5], 0, v[212:213]
	s_mov_b32 m0, s54
	s_nop 0
	global_load_lds_dwordx4 v[224:225], off
	s_waitcnt vmcnt(8)
	s_waitcnt lgkmcnt(0)
	s_barrier
	s_setprio 1
	s_waitcnt lgkmcnt(0)
	v_mfma_f32_16x16x32_bf16 v[140:143], v[88:91], v[160:163], v[140:143]
	v_mfma_f32_16x16x32_bf16 v[136:139], v[96:99], v[160:163], v[136:139]
	v_mfma_f32_16x16x32_bf16 v[124:127], v[88:91], v[168:171], v[124:127]
	v_mfma_f32_16x16x32_bf16 v[120:123], v[96:99], v[168:171], v[120:123]
	v_mfma_f32_16x16x32_bf16 v[108:111], v[88:91], v[176:179], v[108:111]
	v_mfma_f32_16x16x32_bf16 v[104:107], v[96:99], v[176:179], v[104:107]
	v_mfma_f32_16x16x32_bf16 v[76:79], v[88:91], v[184:187], v[76:79]
	v_mfma_f32_16x16x32_bf16 v[72:75], v[96:99], v[184:187], v[72:75]
	v_mfma_f32_16x16x32_bf16 v[140:143], v[92:95], v[164:167], v[140:143]
	v_mfma_f32_16x16x32_bf16 v[136:139], v[100:103], v[164:167], v[136:139]
	v_mfma_f32_16x16x32_bf16 v[124:127], v[92:95], v[172:175], v[124:127]
	v_mfma_f32_16x16x32_bf16 v[120:123], v[100:103], v[172:175], v[120:123]
	v_mfma_f32_16x16x32_bf16 v[108:111], v[92:95], v[180:183], v[108:111]
	v_mfma_f32_16x16x32_bf16 v[104:107], v[100:103], v[180:183], v[104:107]
	v_mfma_f32_16x16x32_bf16 v[76:79], v[92:95], v[188:191], v[76:79]
	v_mfma_f32_16x16x32_bf16 v[72:75], v[100:103], v[188:191], v[72:75]
	s_setprio 0
	s_setprio 1
	v_mfma_f32_16x16x32_bf16 v[132:135], v[144:147], v[160:163], v[132:135]
	v_mfma_f32_16x16x32_bf16 v[128:131], v[152:155], v[160:163], v[128:131]
	v_mfma_f32_16x16x32_bf16 v[116:119], v[144:147], v[168:171], v[116:119]
	v_mfma_f32_16x16x32_bf16 v[112:115], v[152:155], v[168:171], v[112:115]
	v_mfma_f32_16x16x32_bf16 v[84:87], v[144:147], v[176:179], v[84:87]
	v_mfma_f32_16x16x32_bf16 v[80:83], v[152:155], v[176:179], v[80:83]
	v_mfma_f32_16x16x32_bf16 v[68:71], v[144:147], v[184:187], v[68:71]
	v_mfma_f32_16x16x32_bf16 v[64:67], v[152:155], v[184:187], v[64:67]
	v_mfma_f32_16x16x32_bf16 v[132:135], v[148:151], v[164:167], v[132:135]
	v_mfma_f32_16x16x32_bf16 v[128:131], v[156:159], v[164:167], v[128:131]
	v_mfma_f32_16x16x32_bf16 v[116:119], v[148:151], v[172:175], v[116:119]
	v_mfma_f32_16x16x32_bf16 v[112:115], v[156:159], v[172:175], v[112:115]
	v_mfma_f32_16x16x32_bf16 v[84:87], v[148:151], v[180:183], v[84:87]
	v_mfma_f32_16x16x32_bf16 v[80:83], v[156:159], v[180:183], v[80:83]
	v_mfma_f32_16x16x32_bf16 v[68:71], v[148:151], v[188:191], v[68:71]
	v_mfma_f32_16x16x32_bf16 v[64:67], v[156:159], v[188:191], v[64:67]
	s_setprio 0
	s_barrier
	s_add_i32 s4, s28, s2
	v_lshl_add_u64 v[192:193], v[192:193], 0, s[12:13]
	s_mov_b32 m0, s4
	ds_read_b128 v[160:163], v251 offset:49152
	ds_read_b128 v[164:167], v251 offset:50176
	ds_read_b128 v[168:171], v251 offset:51200
	ds_read_b128 v[172:175], v251 offset:52224
	ds_read_b128 v[176:179], v251 offset:53248
	ds_read_b128 v[180:183], v251 offset:54272
	ds_read_b128 v[184:187], v251 offset:55296
	ds_read_b128 v[188:191], v251 offset:56320
	global_load_lds_dwordx4 v[192:193], off
	v_lshl_add_u64 v[192:193], v[194:195], 0, s[12:13]
	s_add_i32 m0, s4, 0x2000
	s_add_i32 s4, s29, s2
	global_load_lds_dwordx4 v[192:193], off
	v_lshl_add_u64 v[192:193], v[196:197], 0, s[12:13]
	s_mov_b32 m0, s4
	s_nop 0
	global_load_lds_dwordx4 v[192:193], off
	v_lshl_add_u64 v[192:193], v[198:199], 0, s[12:13]
	s_add_i32 m0, s4, 0x2000
	s_nop 0
	global_load_lds_dwordx4 v[192:193], off
	v_lshl_add_u64 v[192:193], v[220:221], 0, s[12:13]
	s_mov_b32 m0, s55
	s_nop 0
	global_load_lds_dwordx4 v[192:193], off
	v_lshl_add_u64 v[192:193], v[222:223], 0, s[12:13]
	s_mov_b32 m0, s56
	s_nop 0
	global_load_lds_dwordx4 v[192:193], off
	s_waitcnt vmcnt(8)
	s_waitcnt lgkmcnt(0)
	s_barrier
	s_setprio 1
	s_waitcnt lgkmcnt(0)
	v_mfma_f32_16x16x32_bf16 v[60:63], v[88:91], v[160:163], v[60:63]
	v_mfma_f32_16x16x32_bf16 v[56:59], v[96:99], v[160:163], v[56:59]
	v_mfma_f32_16x16x32_bf16 v[44:47], v[88:91], v[168:171], v[44:47]
	v_mfma_f32_16x16x32_bf16 v[40:43], v[96:99], v[168:171], v[40:43]
	v_mfma_f32_16x16x32_bf16 v[28:31], v[88:91], v[176:179], v[28:31]
	v_mfma_f32_16x16x32_bf16 v[24:27], v[96:99], v[176:179], v[24:27]
	v_mfma_f32_16x16x32_bf16 v[12:15], v[88:91], v[184:187], v[12:15]
	v_mfma_f32_16x16x32_bf16 v[8:11], v[96:99], v[184:187], v[8:11]
	v_mfma_f32_16x16x32_bf16 v[60:63], v[92:95], v[164:167], v[60:63]
	v_mfma_f32_16x16x32_bf16 v[56:59], v[100:103], v[164:167], v[56:59]
	v_mfma_f32_16x16x32_bf16 v[44:47], v[92:95], v[172:175], v[44:47]
	v_mfma_f32_16x16x32_bf16 v[40:43], v[100:103], v[172:175], v[40:43]
	v_mfma_f32_16x16x32_bf16 v[28:31], v[92:95], v[180:183], v[28:31]
	v_mfma_f32_16x16x32_bf16 v[24:27], v[100:103], v[180:183], v[24:27]
	v_mfma_f32_16x16x32_bf16 v[12:15], v[92:95], v[188:191], v[12:15]
	v_mfma_f32_16x16x32_bf16 v[8:11], v[100:103], v[188:191], v[8:11]
	s_setprio 0
	s_setprio 1
	v_mfma_f32_16x16x32_bf16 v[52:55], v[144:147], v[160:163], v[52:55]
	v_mfma_f32_16x16x32_bf16 v[48:51], v[152:155], v[160:163], v[48:51]
	v_mfma_f32_16x16x32_bf16 v[36:39], v[144:147], v[168:171], v[36:39]
	v_mfma_f32_16x16x32_bf16 v[32:35], v[152:155], v[168:171], v[32:35]
	v_mfma_f32_16x16x32_bf16 v[20:23], v[144:147], v[176:179], v[20:23]
	v_mfma_f32_16x16x32_bf16 v[16:19], v[152:155], v[176:179], v[16:19]
	v_mfma_f32_16x16x32_bf16 v[4:7], v[144:147], v[184:187], v[4:7]
	v_mfma_f32_16x16x32_bf16 v[0:3], v[152:155], v[184:187], v[0:3]
	v_mfma_f32_16x16x32_bf16 v[52:55], v[148:151], v[164:167], v[52:55]
	v_mfma_f32_16x16x32_bf16 v[48:51], v[156:159], v[164:167], v[48:51]
	v_mfma_f32_16x16x32_bf16 v[36:39], v[148:151], v[172:175], v[36:39]
	v_mfma_f32_16x16x32_bf16 v[32:35], v[156:159], v[172:175], v[32:35]
	v_mfma_f32_16x16x32_bf16 v[20:23], v[148:151], v[180:183], v[20:23]
	v_mfma_f32_16x16x32_bf16 v[16:19], v[156:159], v[180:183], v[16:19]
	v_mfma_f32_16x16x32_bf16 v[4:7], v[148:151], v[188:191], v[4:7]
	v_mfma_f32_16x16x32_bf16 v[0:3], v[156:159], v[188:191], v[0:3]
	s_setprio 0
	s_barrier
	s_add_u32 s0, s0, 0x100
	s_addc_u32 s1, s1, 0
	s_add_u32 s21, s21, 0x100
	s_addc_u32 s22, s22, 0
	s_cmp_ge_u32 s25, s62
	s_mov_b32 s4, s25
	s_cbranch_scc1 .Lpeel_exit_183
.LBB0_183:
	s_add_i32 s25, s4, 2
	s_add_u32 s28, s0, 0x80
	s_addc_u32 s5, s1, 0
	s_add_i32 s36, 0, 0x10000
	s_cmp_eq_u32 s63, s4
	s_cselect_b32 s5, s49, s5
	s_cselect_b32 s4, s48, s28
	s_cselect_b32 s29, s51, s22
	s_cselect_b32 s28, s50, s21
	s_add_i32 s37, 0, 0x14000
	v_add_u32_e32 v100, s36, v249
	v_add_u32_e32 v156, s37, v249
	ds_read_b128 v[88:91], v100
	ds_read_b128 v[92:95], v100 offset:1024
	ds_read_b128 v[96:99], v100 offset:2048
	ds_read_b128 v[100:103], v100 offset:3072
	s_waitcnt lgkmcnt(0)
	ds_read_b128 v[144:147], v156
	ds_read_b128 v[148:151], v156 offset:1024
	ds_read_b128 v[152:155], v156 offset:2048
	ds_read_b128 v[156:159], v156 offset:3072
	v_lshl_add_u64 v[192:193], s[0:1], 0, v[216:217]
	s_add_i32 m0, s3, 0xc000
	ds_read_b128 v[160:163], v251
	ds_read_b128 v[164:167], v251 offset:1024
	ds_read_b128 v[168:171], v251 offset:2048
	ds_read_b128 v[172:175], v251 offset:3072
	ds_read_b128 v[176:179], v251 offset:4096
	ds_read_b128 v[180:183], v251 offset:5120
	ds_read_b128 v[184:187], v251 offset:6144
	ds_read_b128 v[188:191], v251 offset:7168
	global_load_lds_dwordx4 v[192:193], off
	v_lshl_add_u64 v[192:193], s[0:1], 0, v[218:219]
	s_add_i32 m0, s3, 0xe000
	s_nop 0
	global_load_lds_dwordx4 v[192:193], off
	s_waitcnt vmcnt(8)
	s_waitcnt lgkmcnt(0)
	s_barrier
	s_setprio 1
	s_waitcnt lgkmcnt(0)
	v_mfma_f32_16x16x32_bf16 v[140:143], v[88:91], v[160:163], v[140:143]
	v_mfma_f32_16x16x32_bf16 v[136:139], v[96:99], v[160:163], v[136:139]
	v_mfma_f32_16x16x32_bf16 v[124:127], v[88:91], v[168:171], v[124:127]
	v_mfma_f32_16x16x32_bf16 v[120:123], v[96:99], v[168:171], v[120:123]
	v_mfma_f32_16x16x32_bf16 v[108:111], v[88:91], v[176:179], v[108:111]
	v_mfma_f32_16x16x32_bf16 v[104:107], v[96:99], v[176:179], v[104:107]
	v_mfma_f32_16x16x32_bf16 v[76:79], v[88:91], v[184:187], v[76:79]
	v_mfma_f32_16x16x32_bf16 v[72:75], v[96:99], v[184:187], v[72:75]
	v_mfma_f32_16x16x32_bf16 v[140:143], v[92:95], v[164:167], v[140:143]
	v_mfma_f32_16x16x32_bf16 v[136:139], v[100:103], v[164:167], v[136:139]
	v_mfma_f32_16x16x32_bf16 v[124:127], v[92:95], v[172:175], v[124:127]
	v_mfma_f32_16x16x32_bf16 v[120:123], v[100:103], v[172:175], v[120:123]
	v_mfma_f32_16x16x32_bf16 v[108:111], v[92:95], v[180:183], v[108:111]
	v_mfma_f32_16x16x32_bf16 v[104:107], v[100:103], v[180:183], v[104:107]
	v_mfma_f32_16x16x32_bf16 v[76:79], v[92:95], v[188:191], v[76:79]
	v_mfma_f32_16x16x32_bf16 v[72:75], v[100:103], v[188:191], v[72:75]
	s_setprio 0
	s_setprio 1
	v_mfma_f32_16x16x32_bf16 v[132:135], v[144:147], v[160:163], v[132:135]
	v_mfma_f32_16x16x32_bf16 v[128:131], v[152:155], v[160:163], v[128:131]
	v_mfma_f32_16x16x32_bf16 v[116:119], v[144:147], v[168:171], v[116:119]
	v_mfma_f32_16x16x32_bf16 v[112:115], v[152:155], v[168:171], v[112:115]
	v_mfma_f32_16x16x32_bf16 v[84:87], v[144:147], v[176:179], v[84:87]
	v_mfma_f32_16x16x32_bf16 v[80:83], v[152:155], v[176:179], v[80:83]
	v_mfma_f32_16x16x32_bf16 v[68:71], v[144:147], v[184:187], v[68:71]
	v_mfma_f32_16x16x32_bf16 v[64:67], v[152:155], v[184:187], v[64:67]
	v_mfma_f32_16x16x32_bf16 v[132:135], v[148:151], v[164:167], v[132:135]
	v_mfma_f32_16x16x32_bf16 v[128:131], v[156:159], v[164:167], v[128:131]
	v_mfma_f32_16x16x32_bf16 v[116:119], v[148:151], v[172:175], v[116:119]
	v_mfma_f32_16x16x32_bf16 v[112:115], v[156:159], v[172:175], v[112:115]
	v_mfma_f32_16x16x32_bf16 v[84:87], v[148:151], v[180:183], v[84:87]
	v_mfma_f32_16x16x32_bf16 v[80:83], v[156:159], v[180:183], v[80:83]
	v_mfma_f32_16x16x32_bf16 v[68:71], v[148:151], v[188:191], v[68:71]
	v_mfma_f32_16x16x32_bf16 v[64:67], v[156:159], v[188:191], v[64:67]
	s_setprio 0
	s_barrier
	s_add_i32 s36, s36, s2
	v_lshl_add_u64 v[192:193], s[28:29], 0, v[204:205]
	s_mov_b32 m0, s36
	ds_read_b128 v[160:163], v251 offset:16384
	ds_read_b128 v[164:167], v251 offset:17408
	ds_read_b128 v[168:171], v251 offset:18432
	ds_read_b128 v[172:175], v251 offset:19456
	ds_read_b128 v[176:179], v251 offset:20480
	ds_read_b128 v[180:183], v251 offset:21504
	ds_read_b128 v[184:187], v251 offset:22528
	ds_read_b128 v[188:191], v251 offset:23552
	global_load_lds_dwordx4 v[192:193], off
	s_add_i32 m0, s36, 0x2000
	v_lshl_add_u64 v[194:195], s[28:29], 0, v[210:211]
	s_add_u32 s28, s28, s10
	s_addc_u32 s29, s29, 0
	s_add_i32 s36, s37, s2
	global_load_lds_dwordx4 v[194:195], off
	v_lshl_add_u64 v[196:197], s[28:29], 0, v[204:205]
	s_mov_b32 m0, s36
	v_lshl_add_u64 v[198:199], s[28:29], 0, v[210:211]
	global_load_lds_dwordx4 v[196:197], off
	s_add_i32 m0, s36, 0x2000
	v_lshl_add_u64 v[220:221], s[4:5], 0, v[214:215]
	global_load_lds_dwordx4 v[198:199], off
	s_mov_b32 m0, s3
	v_lshl_add_u64 v[222:223], s[4:5], 0, v[212:213]
	global_load_lds_dwordx4 v[220:221], off
	s_mov_b32 m0, s52
	s_nop 0
	global_load_lds_dwordx4 v[222:223], off
	s_waitcnt vmcnt(8)
	s_waitcnt lgkmcnt(0)
	s_barrier
	s_setprio 1
	s_waitcnt lgkmcnt(0)
	v_mfma_f32_16x16x32_bf16 v[60:63], v[88:91], v[160:163], v[60:63]
	v_mfma_f32_16x16x32_bf16 v[56:59], v[96:99], v[160:163], v[56:59]
	v_mfma_f32_16x16x32_bf16 v[44:47], v[88:91], v[168:171], v[44:47]
	v_mfma_f32_16x16x32_bf16 v[40:43], v[96:99], v[168:171], v[40:43]
	v_mfma_f32_16x16x32_bf16 v[28:31], v[88:91], v[176:179], v[28:31]
	v_mfma_f32_16x16x32_bf16 v[24:27], v[96:99], v[176:179], v[24:27]
	v_mfma_f32_16x16x32_bf16 v[12:15], v[88:91], v[184:187], v[12:15]
	v_mfma_f32_16x16x32_bf16 v[8:11], v[96:99], v[184:187], v[8:11]
	v_mfma_f32_16x16x32_bf16 v[60:63], v[92:95], v[164:167], v[60:63]
	v_mfma_f32_16x16x32_bf16 v[56:59], v[100:103], v[164:167], v[56:59]
	v_mfma_f32_16x16x32_bf16 v[44:47], v[92:95], v[172:175], v[44:47]
	v_mfma_f32_16x16x32_bf16 v[40:43], v[100:103], v[172:175], v[40:43]
	v_mfma_f32_16x16x32_bf16 v[28:31], v[92:95], v[180:183], v[28:31]
	v_mfma_f32_16x16x32_bf16 v[24:27], v[100:103], v[180:183], v[24:27]
	v_mfma_f32_16x16x32_bf16 v[12:15], v[92:95], v[188:191], v[12:15]
	v_mfma_f32_16x16x32_bf16 v[8:11], v[100:103], v[188:191], v[8:11]
	s_setprio 0
	s_setprio 1
	v_mfma_f32_16x16x32_bf16 v[52:55], v[144:147], v[160:163], v[52:55]
	v_mfma_f32_16x16x32_bf16 v[48:51], v[152:155], v[160:163], v[48:51]
	v_mfma_f32_16x16x32_bf16 v[36:39], v[144:147], v[168:171], v[36:39]
	v_mfma_f32_16x16x32_bf16 v[32:35], v[152:155], v[168:171], v[32:35]
	v_mfma_f32_16x16x32_bf16 v[20:23], v[144:147], v[176:179], v[20:23]
	v_mfma_f32_16x16x32_bf16 v[16:19], v[152:155], v[176:179], v[16:19]
	v_mfma_f32_16x16x32_bf16 v[4:7], v[144:147], v[184:187], v[4:7]
	v_mfma_f32_16x16x32_bf16 v[0:3], v[152:155], v[184:187], v[0:3]
	v_mfma_f32_16x16x32_bf16 v[52:55], v[148:151], v[164:167], v[52:55]
	v_mfma_f32_16x16x32_bf16 v[48:51], v[156:159], v[164:167], v[48:51]
	v_mfma_f32_16x16x32_bf16 v[36:39], v[148:151], v[172:175], v[36:39]
	v_mfma_f32_16x16x32_bf16 v[32:35], v[156:159], v[172:175], v[32:35]
	v_mfma_f32_16x16x32_bf16 v[20:23], v[148:151], v[180:183], v[20:23]
	v_mfma_f32_16x16x32_bf16 v[16:19], v[156:159], v[180:183], v[16:19]
	v_mfma_f32_16x16x32_bf16 v[4:7], v[148:151], v[188:191], v[4:7]
	v_mfma_f32_16x16x32_bf16 v[0:3], v[156:159], v[188:191], v[0:3]
	s_setprio 0
	s_barrier
	s_add_i32 s28, 0, 0x18000
	s_add_i32 s29, 0, 0x1c000
	v_add_u32_e32 v100, s28, v249
	v_add_u32_e32 v156, s29, v249
	ds_read_b128 v[88:91], v100
	ds_read_b128 v[92:95], v100 offset:1024
	ds_read_b128 v[96:99], v100 offset:2048
	ds_read_b128 v[100:103], v100 offset:3072
	ds_read_b128 v[144:147], v156
	ds_read_b128 v[148:151], v156 offset:1024
	ds_read_b128 v[152:155], v156 offset:2048
	ds_read_b128 v[156:159], v156 offset:3072
	s_add_u32 s4, s4, s10
	s_addc_u32 s5, s5, 0
	s_mov_b32 m0, s53
	v_lshl_add_u64 v[224:225], s[4:5], 0, v[214:215]
	ds_read_b128 v[160:163], v251 offset:32768
	ds_read_b128 v[164:167], v251 offset:33792
	ds_read_b128 v[168:171], v251 offset:34816
	ds_read_b128 v[172:175], v251 offset:35840
	ds_read_b128 v[176:179], v251 offset:36864
	ds_read_b128 v[180:183], v251 offset:37888
	ds_read_b128 v[184:187], v251 offset:38912
	ds_read_b128 v[188:191], v251 offset:39936
	global_load_lds_dwordx4 v[224:225], off
	v_lshl_add_u64 v[224:225], s[4:5], 0, v[212:213]
	s_mov_b32 m0, s54
	s_nop 0
	global_load_lds_dwordx4 v[224:225], off
	s_waitcnt vmcnt(8)
	s_waitcnt lgkmcnt(0)
	s_barrier
	s_setprio 1
	s_waitcnt lgkmcnt(0)
	v_mfma_f32_16x16x32_bf16 v[140:143], v[88:91], v[160:163], v[140:143]
	v_mfma_f32_16x16x32_bf16 v[136:139], v[96:99], v[160:163], v[136:139]
	v_mfma_f32_16x16x32_bf16 v[124:127], v[88:91], v[168:171], v[124:127]
	v_mfma_f32_16x16x32_bf16 v[120:123], v[96:99], v[168:171], v[120:123]
	v_mfma_f32_16x16x32_bf16 v[108:111], v[88:91], v[176:179], v[108:111]
	v_mfma_f32_16x16x32_bf16 v[104:107], v[96:99], v[176:179], v[104:107]
	v_mfma_f32_16x16x32_bf16 v[76:79], v[88:91], v[184:187], v[76:79]
	v_mfma_f32_16x16x32_bf16 v[72:75], v[96:99], v[184:187], v[72:75]
	v_mfma_f32_16x16x32_bf16 v[140:143], v[92:95], v[164:167], v[140:143]
	v_mfma_f32_16x16x32_bf16 v[136:139], v[100:103], v[164:167], v[136:139]
	v_mfma_f32_16x16x32_bf16 v[124:127], v[92:95], v[172:175], v[124:127]
	v_mfma_f32_16x16x32_bf16 v[120:123], v[100:103], v[172:175], v[120:123]
	v_mfma_f32_16x16x32_bf16 v[108:111], v[92:95], v[180:183], v[108:111]
	v_mfma_f32_16x16x32_bf16 v[104:107], v[100:103], v[180:183], v[104:107]
	v_mfma_f32_16x16x32_bf16 v[76:79], v[92:95], v[188:191], v[76:79]
	v_mfma_f32_16x16x32_bf16 v[72:75], v[100:103], v[188:191], v[72:75]
	s_setprio 0
	s_setprio 1
	v_mfma_f32_16x16x32_bf16 v[132:135], v[144:147], v[160:163], v[132:135]
	v_mfma_f32_16x16x32_bf16 v[128:131], v[152:155], v[160:163], v[128:131]
	v_mfma_f32_16x16x32_bf16 v[116:119], v[144:147], v[168:171], v[116:119]
	v_mfma_f32_16x16x32_bf16 v[112:115], v[152:155], v[168:171], v[112:115]
	v_mfma_f32_16x16x32_bf16 v[84:87], v[144:147], v[176:179], v[84:87]
	v_mfma_f32_16x16x32_bf16 v[80:83], v[152:155], v[176:179], v[80:83]
	v_mfma_f32_16x16x32_bf16 v[68:71], v[144:147], v[184:187], v[68:71]
	v_mfma_f32_16x16x32_bf16 v[64:67], v[152:155], v[184:187], v[64:67]
	v_mfma_f32_16x16x32_bf16 v[132:135], v[148:151], v[164:167], v[132:135]
	v_mfma_f32_16x16x32_bf16 v[128:131], v[156:159], v[164:167], v[128:131]
	v_mfma_f32_16x16x32_bf16 v[116:119], v[148:151], v[172:175], v[116:119]
	v_mfma_f32_16x16x32_bf16 v[112:115], v[156:159], v[172:175], v[112:115]
	v_mfma_f32_16x16x32_bf16 v[84:87], v[148:151], v[180:183], v[84:87]
	v_mfma_f32_16x16x32_bf16 v[80:83], v[156:159], v[180:183], v[80:83]
	v_mfma_f32_16x16x32_bf16 v[68:71], v[148:151], v[188:191], v[68:71]
	v_mfma_f32_16x16x32_bf16 v[64:67], v[156:159], v[188:191], v[64:67]
	s_setprio 0
	s_barrier
	s_add_i32 s4, s28, s2
	v_lshl_add_u64 v[192:193], v[192:193], 0, s[12:13]
	s_mov_b32 m0, s4
	ds_read_b128 v[160:163], v251 offset:49152
	ds_read_b128 v[164:167], v251 offset:50176
	ds_read_b128 v[168:171], v251 offset:51200
	ds_read_b128 v[172:175], v251 offset:52224
	ds_read_b128 v[176:179], v251 offset:53248
	ds_read_b128 v[180:183], v251 offset:54272
	ds_read_b128 v[184:187], v251 offset:55296
	ds_read_b128 v[188:191], v251 offset:56320
	global_load_lds_dwordx4 v[192:193], off
	v_lshl_add_u64 v[192:193], v[194:195], 0, s[12:13]
	s_add_i32 m0, s4, 0x2000
	s_add_i32 s4, s29, s2
	global_load_lds_dwordx4 v[192:193], off
	v_lshl_add_u64 v[192:193], v[196:197], 0, s[12:13]
	s_mov_b32 m0, s4
	s_nop 0
	global_load_lds_dwordx4 v[192:193], off
	v_lshl_add_u64 v[192:193], v[198:199], 0, s[12:13]
	s_add_i32 m0, s4, 0x2000
	s_nop 0
	global_load_lds_dwordx4 v[192:193], off
	v_lshl_add_u64 v[192:193], v[220:221], 0, s[12:13]
	s_mov_b32 m0, s55
	s_nop 0
	global_load_lds_dwordx4 v[192:193], off
	v_lshl_add_u64 v[192:193], v[222:223], 0, s[12:13]
	s_mov_b32 m0, s56
	s_nop 0
	global_load_lds_dwordx4 v[192:193], off
	s_waitcnt vmcnt(8)
	s_waitcnt lgkmcnt(0)
	s_barrier
	s_setprio 1
	s_waitcnt lgkmcnt(0)
	v_mfma_f32_16x16x32_bf16 v[60:63], v[88:91], v[160:163], v[60:63]
	v_mfma_f32_16x16x32_bf16 v[56:59], v[96:99], v[160:163], v[56:59]
	v_mfma_f32_16x16x32_bf16 v[44:47], v[88:91], v[168:171], v[44:47]
	v_mfma_f32_16x16x32_bf16 v[40:43], v[96:99], v[168:171], v[40:43]
	v_mfma_f32_16x16x32_bf16 v[28:31], v[88:91], v[176:179], v[28:31]
	v_mfma_f32_16x16x32_bf16 v[24:27], v[96:99], v[176:179], v[24:27]
	v_mfma_f32_16x16x32_bf16 v[12:15], v[88:91], v[184:187], v[12:15]
	v_mfma_f32_16x16x32_bf16 v[8:11], v[96:99], v[184:187], v[8:11]
	v_mfma_f32_16x16x32_bf16 v[60:63], v[92:95], v[164:167], v[60:63]
	v_mfma_f32_16x16x32_bf16 v[56:59], v[100:103], v[164:167], v[56:59]
	v_mfma_f32_16x16x32_bf16 v[44:47], v[92:95], v[172:175], v[44:47]
	v_mfma_f32_16x16x32_bf16 v[40:43], v[100:103], v[172:175], v[40:43]
	v_mfma_f32_16x16x32_bf16 v[28:31], v[92:95], v[180:183], v[28:31]
	v_mfma_f32_16x16x32_bf16 v[24:27], v[100:103], v[180:183], v[24:27]
	v_mfma_f32_16x16x32_bf16 v[12:15], v[92:95], v[188:191], v[12:15]
	v_mfma_f32_16x16x32_bf16 v[8:11], v[100:103], v[188:191], v[8:11]
	s_setprio 0
	s_setprio 1
	v_mfma_f32_16x16x32_bf16 v[52:55], v[144:147], v[160:163], v[52:55]
	v_mfma_f32_16x16x32_bf16 v[48:51], v[152:155], v[160:163], v[48:51]
	v_mfma_f32_16x16x32_bf16 v[36:39], v[144:147], v[168:171], v[36:39]
	v_mfma_f32_16x16x32_bf16 v[32:35], v[152:155], v[168:171], v[32:35]
	v_mfma_f32_16x16x32_bf16 v[20:23], v[144:147], v[176:179], v[20:23]
	v_mfma_f32_16x16x32_bf16 v[16:19], v[152:155], v[176:179], v[16:19]
	v_mfma_f32_16x16x32_bf16 v[4:7], v[144:147], v[184:187], v[4:7]
	v_mfma_f32_16x16x32_bf16 v[0:3], v[152:155], v[184:187], v[0:3]
	v_mfma_f32_16x16x32_bf16 v[52:55], v[148:151], v[164:167], v[52:55]
	v_mfma_f32_16x16x32_bf16 v[48:51], v[156:159], v[164:167], v[48:51]
	v_mfma_f32_16x16x32_bf16 v[36:39], v[148:151], v[172:175], v[36:39]
	v_mfma_f32_16x16x32_bf16 v[32:35], v[156:159], v[172:175], v[32:35]
	v_mfma_f32_16x16x32_bf16 v[20:23], v[148:151], v[180:183], v[20:23]
	v_mfma_f32_16x16x32_bf16 v[16:19], v[156:159], v[180:183], v[16:19]
	v_mfma_f32_16x16x32_bf16 v[4:7], v[148:151], v[188:191], v[4:7]
	v_mfma_f32_16x16x32_bf16 v[0:3], v[156:159], v[188:191], v[0:3]
	s_setprio 0
	s_barrier
	s_add_u32 s0, s0, 0x100
	s_addc_u32 s1, s1, 0
	s_add_u32 s21, s21, 0x100
	s_addc_u32 s22, s22, 0
	s_cmp_ge_u32 s25, s62
	s_mov_b32 s4, s25
	s_cbranch_scc0 .LBB0_183
.Lpeel_exit_183:
	s_and_b64 vcc, exec, s[40:41]
	s_cbranch_vccz .LBB0_186
	s_barrier

.LBB0_313:
	v_readlane_b32 s36, v209, 51
	v_lshrrev_b32_e32 v9, 1, v98
	v_readlane_b32 s37, v209, 52
	v_and_b32_e32 v9, 24, v9
	s_lshl_b64 s[36:37], s[36:37], 2
	v_and_b32_e32 v8, 15, v98
	v_lshlrev_b32_e32 v10, 1, v9
	s_add_u32 s52, s20, s36
	v_lshl_or_b32 v157, s35, 6, v8
	v_lshl_or_b32 v10, v8, 6, v10
	v_lshlrev_b32_e32 v8, 2, v8
	s_addc_u32 s53, s21, s37
	s_lshl_b32 s20, s35, 13
	v_and_b32_e32 v11, 32, v8
	v_bitop3_b32 v12, v10, s20, v11 bitop3:0xde
	s_lshl_b32 s20, s34, 5
	s_and_b32 s34, s20, 0x60
	s_add_i32 m0, s7, 0x18000
	v_lshl_add_u64 v[2:3], v[2:3], 0, s[12:13]
	s_lshl_b32 s20, s34, 7
	s_waitcnt vmcnt(2)
	s_barrier
	global_load_lds_dwordx4 v[2:3], off
	v_lshl_add_u64 v[2:3], v[4:5], 0, s[12:13]
	s_add_i32 m0, s7, 0x1a000
	s_add_i32 s54, s7, 0x8000
	s_add_i32 s55, s7, 0xa000
	v_bitop3_b32 v159, v10, s20, v11 bitop3:0xde
	global_load_lds_dwordx4 v[2:3], off
	v_lshl_add_u64 v[0:1], v[0:1], 0, s[12:13]
	s_mov_b32 m0, s54
	s_add_u32 s20, s0, 0x80080
	global_load_lds_dwordx4 v[0:1], off
	v_lshl_add_u64 v[0:1], v[6:7], 0, s[12:13]
	s_mov_b32 m0, s55
	s_addc_u32 s21, s1, 0
	global_load_lds_dwordx4 v[0:1], off
	s_add_i32 m0, s7, 0x1c000
	v_lshl_add_u64 v[0:1], s[20:21], 0, v[204:205]
	global_load_lds_dwordx4 v[0:1], off
	v_lshl_add_u64 v[0:1], s[20:21], 0, v[148:149]
	s_add_i32 m0, s7, 0x1e000
	s_cmpk_lt_u32 s25, 0x100
	global_load_lds_dwordx4 v[0:1], off
	v_lshlrev_b32_e32 v0, 15, v99
	v_and_b32_e32 v0, 0xffff0000, v0
	v_lshl_add_u32 v0, v100, 12, v0
	v_and_b32_e32 v1, 1, v99
	v_lshl_or_b32 v0, v1, 6, v0
	v_lshl_add_u32 v150, v101, 1, v0
	v_lshlrev_b32_e32 v0, 15, v102
	v_and_b32_e32 v0, 0xffff0000, v0
	s_cselect_b64 s[20:21], -1, 0
	s_and_b32 s25, s25, 0xffffff00
	v_lshl_add_u32 v0, v103, 12, v0
	v_and_b32_e32 v1, 1, v102
	s_waitcnt vmcnt(6)
	s_add_i32 s25, s25, 0
	v_lshl_or_b32 v0, v1, 6, v0
	s_add_i32 s25, s25, 0x20000
	v_lshl_add_u32 v152, v104, 1, v0
	v_add_u32_e32 v161, s25, v8
	v_or_b32_e32 v163, s34, v9
	v_mov_b32_e32 v151, v205
	v_mov_b32_e32 v153, v205
	s_mov_b32 s56, 0
	v_add_u32_e32 v165, 0, v12
	s_mov_b32 s64, 0
	s_barrier
	s_branch .LBB0_315
.LBB0_314:
	s_mov_b32 s6, s34
	s_mov_b32 s8, s38
	s_mov_b32 s56, s57
	s_mov_b64 s[2:3], s[42:43]
	s_mov_b32 s64, s65
	s_andn2_b64 vcc, exec, s[60:61]
	s_mov_b64 s[0:1], s[40:41]
	s_cbranch_vccz .LBB0_325

.LBB0_317:
	s_add_u32 s25, s0, 0x100
	s_addc_u32 s66, s1, 0
	s_ashr_i32 s39, s38, 31
	s_lshl_b64 s[36:37], s[38:39], 20
	s_add_u32 s42, s16, s36
	s_addc_u32 s43, s17, s37
	s_and_b64 s[36:37], s[62:63], exec
	s_cselect_b32 s39, s43, s3
	s_cselect_b32 s67, s42, s2
	s_ashr_i32 s35, s34, 31
	s_lshl_b64 s[36:37], s[34:35], 20
	s_add_u32 s40, s46, s36
	s_addc_u32 s41, s47, s37
	s_and_b64 s[36:37], s[62:63], exec
	s_cselect_b32 s35, s41, s1
	s_cselect_b32 s70, s40, s0
	s_add_u32 s0, s2, 0x80080
	s_addc_u32 s1, s3, 0
	v_lshl_add_u64 v[128:129], s[0:1], 0, v[150:151]
	v_lshl_add_u64 v[130:131], s[0:1], 0, v[152:153]
	s_mov_b32 s71, -2
	s_mov_b64 s[0:1], 0
	s_add_u32 s36, s2, s0
	s_addc_u32 s37, s3, s1
	s_add_u32 s36, s36, 0x100
	s_addc_u32 s37, s37, 0
	s_add_u32 s72, s25, s0
	s_addc_u32 s73, s66, s1
	s_add_i32 s74, 0, 0x10000
	s_cmpk_eq_i32 s0, 0xf00
	s_cselect_b32 s45, s39, s37
	s_cselect_b32 s44, s67, s36
	v_add_u32_e32 v154, s74, v159
	s_cselect_b32 s37, s35, s73
	s_cselect_b32 s36, s70, s72
	s_add_i32 s75, 0, 0x14000
	ds_read_b128 v[132:135], v154
	ds_read_b128 v[136:139], v154 offset:1024
	ds_read_b128 v[140:143], v154 offset:2048
	ds_read_b128 v[166:169], v154 offset:3072
	v_add_u32_e32 v154, s75, v159
	ds_read_b128 v[170:173], v154
	ds_read_b128 v[174:177], v154 offset:1024
	ds_read_b128 v[178:181], v154 offset:2048
	ds_read_b128 v[182:185], v154 offset:3072
	v_lshl_add_u64 v[154:155], v[128:129], 0, s[0:1]
	s_add_i32 m0, s7, 0xc000
	ds_read_b128 v[186:189], v165
	ds_read_b128 v[190:193], v165 offset:1024
	ds_read_b128 v[194:197], v165 offset:2048
	ds_read_b128 v[210:213], v165 offset:3072
	ds_read_b128 v[214:217], v165 offset:4096
	ds_read_b128 v[218:221], v165 offset:5120
	ds_read_b128 v[222:225], v165 offset:6144
	ds_read_b128 v[226:229], v165 offset:7168
	global_load_lds_dwordx4 v[154:155], off
	v_lshl_add_u64 v[154:155], v[130:131], 0, s[0:1]
	s_add_i32 m0, s7, 0xe000
	s_nop 0
	global_load_lds_dwordx4 v[154:155], off
	s_waitcnt vmcnt(8)
	s_waitcnt lgkmcnt(0)
	s_barrier
	s_setprio 1
	s_waitcnt lgkmcnt(0)
	v_mfma_f32_16x16x32_bf16 v[124:127], v[132:135], v[186:189], 0
	v_mfma_f32_16x16x32_bf16 v[120:123], v[140:143], v[186:189], 0
	v_mfma_f32_16x16x32_bf16 v[116:119], v[132:135], v[194:197], 0
	v_mfma_f32_16x16x32_bf16 v[112:115], v[140:143], v[194:197], 0
	v_mfma_f32_16x16x32_bf16 v[108:111], v[132:135], v[214:217], 0
	v_mfma_f32_16x16x32_bf16 v[104:107], v[140:143], v[214:217], 0
	v_mfma_f32_16x16x32_bf16 v[100:103], v[132:135], v[222:225], 0
	v_mfma_f32_16x16x32_bf16 v[96:99], v[140:143], v[222:225], 0
	v_mfma_f32_16x16x32_bf16 v[124:127], v[136:139], v[190:193], v[124:127]
	v_mfma_f32_16x16x32_bf16 v[120:123], v[166:169], v[190:193], v[120:123]
	v_mfma_f32_16x16x32_bf16 v[116:119], v[136:139], v[210:213], v[116:119]
	v_mfma_f32_16x16x32_bf16 v[112:115], v[166:169], v[210:213], v[112:115]
	v_mfma_f32_16x16x32_bf16 v[108:111], v[136:139], v[218:221], v[108:111]
	v_mfma_f32_16x16x32_bf16 v[104:107], v[166:169], v[218:221], v[104:107]
	v_mfma_f32_16x16x32_bf16 v[100:103], v[136:139], v[226:229], v[100:103]
	v_mfma_f32_16x16x32_bf16 v[96:99], v[166:169], v[226:229], v[96:99]
	s_setprio 0
	s_setprio 1
	v_mfma_f32_16x16x32_bf16 v[92:95], v[170:173], v[186:189], 0
	v_mfma_f32_16x16x32_bf16 v[88:91], v[178:181], v[186:189], 0
	v_mfma_f32_16x16x32_bf16 v[84:87], v[170:173], v[194:197], 0
	v_mfma_f32_16x16x32_bf16 v[80:83], v[178:181], v[194:197], 0
	v_mfma_f32_16x16x32_bf16 v[76:79], v[170:173], v[214:217], 0
	v_mfma_f32_16x16x32_bf16 v[72:75], v[178:181], v[214:217], 0
	v_mfma_f32_16x16x32_bf16 v[68:71], v[170:173], v[222:225], 0
	v_mfma_f32_16x16x32_bf16 v[64:67], v[178:181], v[222:225], 0
	v_mfma_f32_16x16x32_bf16 v[92:95], v[174:177], v[190:193], v[92:95]
	v_mfma_f32_16x16x32_bf16 v[88:91], v[182:185], v[190:193], v[88:91]
	v_mfma_f32_16x16x32_bf16 v[84:87], v[174:177], v[210:213], v[84:87]
	v_mfma_f32_16x16x32_bf16 v[80:83], v[182:185], v[210:213], v[80:83]
	v_mfma_f32_16x16x32_bf16 v[76:79], v[174:177], v[218:221], v[76:79]
	v_mfma_f32_16x16x32_bf16 v[72:75], v[182:185], v[218:221], v[72:75]
	v_mfma_f32_16x16x32_bf16 v[68:71], v[174:177], v[226:229], v[68:71]
	v_mfma_f32_16x16x32_bf16 v[64:67], v[182:185], v[226:229], v[64:67]
	s_setprio 0
	s_barrier
	s_add_i32 s72, s74, s29
	v_lshl_add_u64 v[154:155], s[36:37], 0, v[204:205]
	s_mov_b32 m0, s72
	ds_read_b128 v[186:189], v165 offset:16384
	ds_read_b128 v[190:193], v165 offset:17408
	ds_read_b128 v[194:197], v165 offset:18432
	ds_read_b128 v[210:213], v165 offset:19456
	ds_read_b128 v[214:217], v165 offset:20480
	ds_read_b128 v[218:221], v165 offset:21504
	ds_read_b128 v[222:225], v165 offset:22528
	ds_read_b128 v[226:229], v165 offset:23552
	global_load_lds_dwordx4 v[154:155], off
	s_add_i32 m0, s72, 0x2000
	s_add_u32 s72, s36, 0x80000
	v_lshl_add_u64 v[198:199], s[36:37], 0, v[148:149]
	s_addc_u32 s73, s37, 0
	s_add_i32 s74, s75, s29
	global_load_lds_dwordx4 v[198:199], off
	v_lshl_add_u64 v[230:231], s[72:73], 0, v[204:205]
	s_mov_b32 m0, s74
	v_lshl_add_u64 v[232:233], s[44:45], 0, v[146:147]
	global_load_lds_dwordx4 v[230:231], off
	v_lshl_add_u64 v[230:231], s[72:73], 0, v[148:149]
	s_add_i32 m0, s74, 0x2000
	s_nop 0
	global_load_lds_dwordx4 v[230:231], off
	v_lshl_add_u64 v[230:231], s[44:45], 0, v[144:145]
	s_mov_b32 m0, s7
	s_nop 0
	global_load_lds_dwordx4 v[230:231], off
	s_mov_b32 m0, s9
	s_nop 0
	global_load_lds_dwordx4 v[232:233], off
	s_waitcnt vmcnt(8)
	s_waitcnt lgkmcnt(0)
	s_barrier
	s_setprio 1
	s_waitcnt lgkmcnt(0)
	v_mfma_f32_16x16x32_bf16 v[60:63], v[132:135], v[186:189], 0
	v_mfma_f32_16x16x32_bf16 v[56:59], v[140:143], v[186:189], 0
	v_mfma_f32_16x16x32_bf16 v[52:55], v[132:135], v[194:197], 0
	v_mfma_f32_16x16x32_bf16 v[48:51], v[140:143], v[194:197], 0
	v_mfma_f32_16x16x32_bf16 v[44:47], v[132:135], v[214:217], 0
	v_mfma_f32_16x16x32_bf16 v[40:43], v[140:143], v[214:217], 0
	v_mfma_f32_16x16x32_bf16 v[36:39], v[132:135], v[222:225], 0
	v_mfma_f32_16x16x32_bf16 v[32:35], v[140:143], v[222:225], 0
	v_mfma_f32_16x16x32_bf16 v[60:63], v[136:139], v[190:193], v[60:63]
	v_mfma_f32_16x16x32_bf16 v[56:59], v[166:169], v[190:193], v[56:59]
	v_mfma_f32_16x16x32_bf16 v[52:55], v[136:139], v[210:213], v[52:55]
	v_mfma_f32_16x16x32_bf16 v[48:51], v[166:169], v[210:213], v[48:51]
	v_mfma_f32_16x16x32_bf16 v[44:47], v[136:139], v[218:221], v[44:47]
	v_mfma_f32_16x16x32_bf16 v[40:43], v[166:169], v[218:221], v[40:43]
	v_mfma_f32_16x16x32_bf16 v[36:39], v[136:139], v[226:229], v[36:39]
	v_mfma_f32_16x16x32_bf16 v[32:35], v[166:169], v[226:229], v[32:35]
	s_setprio 0
	s_setprio 1
	v_mfma_f32_16x16x32_bf16 v[28:31], v[170:173], v[186:189], 0
	v_mfma_f32_16x16x32_bf16 v[24:27], v[178:181], v[186:189], 0
	v_mfma_f32_16x16x32_bf16 v[20:23], v[170:173], v[194:197], 0
	v_mfma_f32_16x16x32_bf16 v[16:19], v[178:181], v[194:197], 0
	v_mfma_f32_16x16x32_bf16 v[12:15], v[170:173], v[214:217], 0
	v_mfma_f32_16x16x32_bf16 v[8:11], v[178:181], v[214:217], 0
	v_mfma_f32_16x16x32_bf16 v[4:7], v[170:173], v[222:225], 0
	v_mfma_f32_16x16x32_bf16 v[0:3], v[178:181], v[222:225], 0
	v_mfma_f32_16x16x32_bf16 v[28:31], v[174:177], v[190:193], v[28:31]
	v_mfma_f32_16x16x32_bf16 v[24:27], v[182:185], v[190:193], v[24:27]
	v_mfma_f32_16x16x32_bf16 v[20:23], v[174:177], v[210:213], v[20:23]
	v_mfma_f32_16x16x32_bf16 v[16:19], v[182:185], v[210:213], v[16:19]
	v_mfma_f32_16x16x32_bf16 v[12:15], v[174:177], v[218:221], v[12:15]
	v_mfma_f32_16x16x32_bf16 v[8:11], v[182:185], v[218:221], v[8:11]
	v_mfma_f32_16x16x32_bf16 v[4:7], v[174:177], v[226:229], v[4:7]
	v_mfma_f32_16x16x32_bf16 v[0:3], v[182:185], v[226:229], v[0:3]
	s_setprio 0
	s_barrier
	s_add_i32 s72, 0, 0x18000
	v_add_u32_e32 v156, s72, v159
	s_add_i32 s73, 0, 0x1c000
	ds_read_b128 v[132:135], v156
	ds_read_b128 v[136:139], v156 offset:1024
	ds_read_b128 v[140:143], v156 offset:2048
	ds_read_b128 v[166:169], v156 offset:3072
	v_add_u32_e32 v156, s73, v159
	ds_read_b128 v[170:173], v156
	ds_read_b128 v[174:177], v156 offset:1024
	ds_read_b128 v[178:181], v156 offset:2048
	ds_read_b128 v[182:185], v156 offset:3072
	s_add_u32 s44, s44, 0x80000
	s_addc_u32 s45, s45, 0
	s_mov_b32 m0, s49
	v_lshl_add_u64 v[248:249], s[44:45], 0, v[144:145]
	ds_read_b128 v[186:189], v165 offset:32768
	ds_read_b128 v[190:193], v165 offset:33792
	ds_read_b128 v[194:197], v165 offset:34816
	ds_read_b128 v[210:213], v165 offset:35840
	ds_read_b128 v[214:217], v165 offset:36864
	ds_read_b128 v[218:221], v165 offset:37888
	ds_read_b128 v[222:225], v165 offset:38912
	ds_read_b128 v[226:229], v165 offset:39936
	global_load_lds_dwordx4 v[248:249], off
	v_lshl_add_u64 v[248:249], s[44:45], 0, v[146:147]
	s_mov_b32 m0, s50
	s_nop 0
	global_load_lds_dwordx4 v[248:249], off
	s_waitcnt vmcnt(8)
	s_waitcnt lgkmcnt(0)
	s_barrier
	s_setprio 1
	s_waitcnt lgkmcnt(0)
	v_mfma_f32_16x16x32_bf16 v[124:127], v[132:135], v[186:189], v[124:127]
	v_mfma_f32_16x16x32_bf16 v[120:123], v[140:143], v[186:189], v[120:123]
	v_mfma_f32_16x16x32_bf16 v[116:119], v[132:135], v[194:197], v[116:119]
	v_mfma_f32_16x16x32_bf16 v[112:115], v[140:143], v[194:197], v[112:115]
	v_mfma_f32_16x16x32_bf16 v[108:111], v[132:135], v[214:217], v[108:111]
	v_mfma_f32_16x16x32_bf16 v[104:107], v[140:143], v[214:217], v[104:107]
	v_mfma_f32_16x16x32_bf16 v[100:103], v[132:135], v[222:225], v[100:103]
	v_mfma_f32_16x16x32_bf16 v[96:99], v[140:143], v[222:225], v[96:99]
	v_mfma_f32_16x16x32_bf16 v[124:127], v[136:139], v[190:193], v[124:127]
	v_mfma_f32_16x16x32_bf16 v[120:123], v[166:169], v[190:193], v[120:123]
	v_mfma_f32_16x16x32_bf16 v[116:119], v[136:139], v[210:213], v[116:119]
	v_mfma_f32_16x16x32_bf16 v[112:115], v[166:169], v[210:213], v[112:115]
	v_mfma_f32_16x16x32_bf16 v[108:111], v[136:139], v[218:221], v[108:111]
	v_mfma_f32_16x16x32_bf16 v[104:107], v[166:169], v[218:221], v[104:107]
	v_mfma_f32_16x16x32_bf16 v[100:103], v[136:139], v[226:229], v[100:103]
	v_mfma_f32_16x16x32_bf16 v[96:99], v[166:169], v[226:229], v[96:99]
	s_setprio 0
	s_setprio 1
	v_mfma_f32_16x16x32_bf16 v[92:95], v[170:173], v[186:189], v[92:95]
	v_mfma_f32_16x16x32_bf16 v[88:91], v[178:181], v[186:189], v[88:91]
	v_mfma_f32_16x16x32_bf16 v[84:87], v[170:173], v[194:197], v[84:87]
	v_mfma_f32_16x16x32_bf16 v[80:83], v[178:181], v[194:197], v[80:83]
	v_mfma_f32_16x16x32_bf16 v[76:79], v[170:173], v[214:217], v[76:79]
	v_mfma_f32_16x16x32_bf16 v[72:75], v[178:181], v[214:217], v[72:75]
	v_mfma_f32_16x16x32_bf16 v[68:71], v[170:173], v[222:225], v[68:71]
	v_mfma_f32_16x16x32_bf16 v[64:67], v[178:181], v[222:225], v[64:67]
	v_mfma_f32_16x16x32_bf16 v[92:95], v[174:177], v[190:193], v[92:95]
	v_mfma_f32_16x16x32_bf16 v[88:91], v[182:185], v[190:193], v[88:91]
	v_mfma_f32_16x16x32_bf16 v[84:87], v[174:177], v[210:213], v[84:87]
	v_mfma_f32_16x16x32_bf16 v[80:83], v[182:185], v[210:213], v[80:83]
	v_mfma_f32_16x16x32_bf16 v[76:79], v[174:177], v[218:221], v[76:79]
	v_mfma_f32_16x16x32_bf16 v[72:75], v[182:185], v[218:221], v[72:75]
	v_mfma_f32_16x16x32_bf16 v[68:71], v[174:177], v[226:229], v[68:71]
	v_mfma_f32_16x16x32_bf16 v[64:67], v[182:185], v[226:229], v[64:67]
	s_setprio 0
	s_barrier
	s_add_i32 s44, s72, s29
	v_lshl_add_u64 v[154:155], v[154:155], 0, s[12:13]
	s_mov_b32 m0, s44
	ds_read_b128 v[186:189], v165 offset:49152
	ds_read_b128 v[190:193], v165 offset:50176
	ds_read_b128 v[194:197], v165 offset:51200
	ds_read_b128 v[210:213], v165 offset:52224
	ds_read_b128 v[214:217], v165 offset:53248
	ds_read_b128 v[218:221], v165 offset:54272
	ds_read_b128 v[222:225], v165 offset:55296
	ds_read_b128 v[226:229], v165 offset:56320
	global_load_lds_dwordx4 v[154:155], off
	s_add_i32 m0, s44, 0x2000
	s_add_u32 s36, s36, 0x80080
	v_lshl_add_u64 v[154:155], v[198:199], 0, s[12:13]
	s_addc_u32 s37, s37, 0
	s_add_i32 s44, s73, s29
	global_load_lds_dwordx4 v[154:155], off
	v_lshl_add_u64 v[154:155], s[36:37], 0, v[204:205]
	s_mov_b32 m0, s44
	s_nop 0
	global_load_lds_dwordx4 v[154:155], off
	v_lshl_add_u64 v[154:155], s[36:37], 0, v[148:149]
	s_add_i32 m0, s44, 0x2000
	s_nop 0
	global_load_lds_dwordx4 v[154:155], off
	v_lshl_add_u64 v[154:155], v[230:231], 0, s[12:13]
	s_mov_b32 m0, s54
	s_nop 0
	global_load_lds_dwordx4 v[154:155], off
	v_lshl_add_u64 v[154:155], v[232:233], 0, s[12:13]
	s_mov_b32 m0, s55
	s_nop 0
	global_load_lds_dwordx4 v[154:155], off
	s_waitcnt vmcnt(8)
	s_waitcnt lgkmcnt(0)
	s_barrier
	s_setprio 1
	s_waitcnt lgkmcnt(0)
	v_mfma_f32_16x16x32_bf16 v[60:63], v[132:135], v[186:189], v[60:63]
	v_mfma_f32_16x16x32_bf16 v[56:59], v[140:143], v[186:189], v[56:59]
	v_mfma_f32_16x16x32_bf16 v[52:55], v[132:135], v[194:197], v[52:55]
	v_mfma_f32_16x16x32_bf16 v[48:51], v[140:143], v[194:197], v[48:51]
	v_mfma_f32_16x16x32_bf16 v[44:47], v[132:135], v[214:217], v[44:47]
	v_mfma_f32_16x16x32_bf16 v[40:43], v[140:143], v[214:217], v[40:43]
	v_mfma_f32_16x16x32_bf16 v[36:39], v[132:135], v[222:225], v[36:39]
	v_mfma_f32_16x16x32_bf16 v[32:35], v[140:143], v[222:225], v[32:35]
	v_mfma_f32_16x16x32_bf16 v[60:63], v[136:139], v[190:193], v[60:63]
	v_mfma_f32_16x16x32_bf16 v[56:59], v[166:169], v[190:193], v[56:59]
	v_mfma_f32_16x16x32_bf16 v[52:55], v[136:139], v[210:213], v[52:55]
	v_mfma_f32_16x16x32_bf16 v[48:51], v[166:169], v[210:213], v[48:51]
	v_mfma_f32_16x16x32_bf16 v[44:47], v[136:139], v[218:221], v[44:47]
	v_mfma_f32_16x16x32_bf16 v[40:43], v[166:169], v[218:221], v[40:43]
	v_mfma_f32_16x16x32_bf16 v[36:39], v[136:139], v[226:229], v[36:39]
	v_mfma_f32_16x16x32_bf16 v[32:35], v[166:169], v[226:229], v[32:35]
	s_setprio 0
	s_setprio 1
	v_mfma_f32_16x16x32_bf16 v[28:31], v[170:173], v[186:189], v[28:31]
	v_mfma_f32_16x16x32_bf16 v[24:27], v[178:181], v[186:189], v[24:27]
	v_mfma_f32_16x16x32_bf16 v[20:23], v[170:173], v[194:197], v[20:23]
	v_mfma_f32_16x16x32_bf16 v[16:19], v[178:181], v[194:197], v[16:19]
	v_mfma_f32_16x16x32_bf16 v[12:15], v[170:173], v[214:217], v[12:15]
	v_mfma_f32_16x16x32_bf16 v[8:11], v[178:181], v[214:217], v[8:11]
	v_mfma_f32_16x16x32_bf16 v[4:7], v[170:173], v[222:225], v[4:7]
	v_mfma_f32_16x16x32_bf16 v[0:3], v[178:181], v[222:225], v[0:3]
	v_mfma_f32_16x16x32_bf16 v[28:31], v[174:177], v[190:193], v[28:31]
	v_mfma_f32_16x16x32_bf16 v[24:27], v[182:185], v[190:193], v[24:27]
	v_mfma_f32_16x16x32_bf16 v[20:23], v[174:177], v[210:213], v[20:23]
	v_mfma_f32_16x16x32_bf16 v[16:19], v[182:185], v[210:213], v[16:19]
	v_mfma_f32_16x16x32_bf16 v[12:15], v[174:177], v[218:221], v[12:15]
	v_mfma_f32_16x16x32_bf16 v[8:11], v[182:185], v[218:221], v[8:11]
	v_mfma_f32_16x16x32_bf16 v[4:7], v[174:177], v[226:229], v[4:7]
	v_mfma_f32_16x16x32_bf16 v[0:3], v[182:185], v[226:229], v[0:3]
	s_setprio 0
	s_barrier
	s_add_i32 s71, s71, 2
	s_add_u32 s0, s0, 0x100
	s_addc_u32 s1, s1, 0
	s_cmp_gt_u32 s71, 29
	s_cbranch_scc1 .Lpeel_exit_318
.LBB0_318:
	s_add_u32 s36, s2, s0
	s_addc_u32 s37, s3, s1
	s_add_u32 s36, s36, 0x100
	s_addc_u32 s37, s37, 0
	s_add_u32 s72, s25, s0
	s_addc_u32 s73, s66, s1
	s_add_i32 s74, 0, 0x10000
	s_cmpk_eq_i32 s0, 0xf00
	s_cselect_b32 s45, s39, s37
	s_cselect_b32 s44, s67, s36
	v_add_u32_e32 v154, s74, v159
	s_cselect_b32 s37, s35, s73
	s_cselect_b32 s36, s70, s72
	s_add_i32 s75, 0, 0x14000
	ds_read_b128 v[132:135], v154
	ds_read_b128 v[136:139], v154 offset:1024
	ds_read_b128 v[140:143], v154 offset:2048
	ds_read_b128 v[166:169], v154 offset:3072
	v_add_u32_e32 v154, s75, v159
	ds_read_b128 v[170:173], v154
	ds_read_b128 v[174:177], v154 offset:1024
	ds_read_b128 v[178:181], v154 offset:2048
	ds_read_b128 v[182:185], v154 offset:3072
	v_lshl_add_u64 v[154:155], v[128:129], 0, s[0:1]
	s_add_i32 m0, s7, 0xc000
	ds_read_b128 v[186:189], v165
	ds_read_b128 v[190:193], v165 offset:1024
	ds_read_b128 v[194:197], v165 offset:2048
	ds_read_b128 v[210:213], v165 offset:3072
	ds_read_b128 v[214:217], v165 offset:4096
	ds_read_b128 v[218:221], v165 offset:5120
	ds_read_b128 v[222:225], v165 offset:6144
	ds_read_b128 v[226:229], v165 offset:7168
	global_load_lds_dwordx4 v[154:155], off
	v_lshl_add_u64 v[154:155], v[130:131], 0, s[0:1]
	s_add_i32 m0, s7, 0xe000
	s_nop 0
	global_load_lds_dwordx4 v[154:155], off
	s_waitcnt vmcnt(8)
	s_waitcnt lgkmcnt(0)
	s_barrier
	s_setprio 1
	s_waitcnt lgkmcnt(0)
	v_mfma_f32_16x16x32_bf16 v[124:127], v[132:135], v[186:189], v[124:127]
	v_mfma_f32_16x16x32_bf16 v[120:123], v[140:143], v[186:189], v[120:123]
	v_mfma_f32_16x16x32_bf16 v[116:119], v[132:135], v[194:197], v[116:119]
	v_mfma_f32_16x16x32_bf16 v[112:115], v[140:143], v[194:197], v[112:115]
	v_mfma_f32_16x16x32_bf16 v[108:111], v[132:135], v[214:217], v[108:111]
	v_mfma_f32_16x16x32_bf16 v[104:107], v[140:143], v[214:217], v[104:107]
	v_mfma_f32_16x16x32_bf16 v[100:103], v[132:135], v[222:225], v[100:103]
	v_mfma_f32_16x16x32_bf16 v[96:99], v[140:143], v[222:225], v[96:99]
	v_mfma_f32_16x16x32_bf16 v[124:127], v[136:139], v[190:193], v[124:127]
	v_mfma_f32_16x16x32_bf16 v[120:123], v[166:169], v[190:193], v[120:123]
	v_mfma_f32_16x16x32_bf16 v[116:119], v[136:139], v[210:213], v[116:119]
	v_mfma_f32_16x16x32_bf16 v[112:115], v[166:169], v[210:213], v[112:115]
	v_mfma_f32_16x16x32_bf16 v[108:111], v[136:139], v[218:221], v[108:111]
	v_mfma_f32_16x16x32_bf16 v[104:107], v[166:169], v[218:221], v[104:107]
	v_mfma_f32_16x16x32_bf16 v[100:103], v[136:139], v[226:229], v[100:103]
	v_mfma_f32_16x16x32_bf16 v[96:99], v[166:169], v[226:229], v[96:99]
	s_setprio 0
	s_setprio 1
	v_mfma_f32_16x16x32_bf16 v[92:95], v[170:173], v[186:189], v[92:95]
	v_mfma_f32_16x16x32_bf16 v[88:91], v[178:181], v[186:189], v[88:91]
	v_mfma_f32_16x16x32_bf16 v[84:87], v[170:173], v[194:197], v[84:87]
	v_mfma_f32_16x16x32_bf16 v[80:83], v[178:181], v[194:197], v[80:83]
	v_mfma_f32_16x16x32_bf16 v[76:79], v[170:173], v[214:217], v[76:79]
	v_mfma_f32_16x16x32_bf16 v[72:75], v[178:181], v[214:217], v[72:75]
	v_mfma_f32_16x16x32_bf16 v[68:71], v[170:173], v[222:225], v[68:71]
	v_mfma_f32_16x16x32_bf16 v[64:67], v[178:181], v[222:225], v[64:67]
	v_mfma_f32_16x16x32_bf16 v[92:95], v[174:177], v[190:193], v[92:95]
	v_mfma_f32_16x16x32_bf16 v[88:91], v[182:185], v[190:193], v[88:91]
	v_mfma_f32_16x16x32_bf16 v[84:87], v[174:177], v[210:213], v[84:87]
	v_mfma_f32_16x16x32_bf16 v[80:83], v[182:185], v[210:213], v[80:83]
	v_mfma_f32_16x16x32_bf16 v[76:79], v[174:177], v[218:221], v[76:79]
	v_mfma_f32_16x16x32_bf16 v[72:75], v[182:185], v[218:221], v[72:75]
	v_mfma_f32_16x16x32_bf16 v[68:71], v[174:177], v[226:229], v[68:71]
	v_mfma_f32_16x16x32_bf16 v[64:67], v[182:185], v[226:229], v[64:67]
	s_setprio 0
	s_barrier
	s_add_i32 s72, s74, s29
	v_lshl_add_u64 v[154:155], s[36:37], 0, v[204:205]
	s_mov_b32 m0, s72
	ds_read_b128 v[186:189], v165 offset:16384
	ds_read_b128 v[190:193], v165 offset:17408
	ds_read_b128 v[194:197], v165 offset:18432
	ds_read_b128 v[210:213], v165 offset:19456
	ds_read_b128 v[214:217], v165 offset:20480
	ds_read_b128 v[218:221], v165 offset:21504
	ds_read_b128 v[222:225], v165 offset:22528
	ds_read_b128 v[226:229], v165 offset:23552
	global_load_lds_dwordx4 v[154:155], off
	s_add_i32 m0, s72, 0x2000
	s_add_u32 s72, s36, 0x80000
	v_lshl_add_u64 v[198:199], s[36:37], 0, v[148:149]
	s_addc_u32 s73, s37, 0
	s_add_i32 s74, s75, s29
	global_load_lds_dwordx4 v[198:199], off
	v_lshl_add_u64 v[230:231], s[72:73], 0, v[204:205]
	s_mov_b32 m0, s74
	v_lshl_add_u64 v[232:233], s[44:45], 0, v[146:147]
	global_load_lds_dwordx4 v[230:231], off
	v_lshl_add_u64 v[230:231], s[72:73], 0, v[148:149]
	s_add_i32 m0, s74, 0x2000
	s_nop 0
	global_load_lds_dwordx4 v[230:231], off
	v_lshl_add_u64 v[230:231], s[44:45], 0, v[144:145]
	s_mov_b32 m0, s7
	s_nop 0
	global_load_lds_dwordx4 v[230:231], off
	s_mov_b32 m0, s9
	s_nop 0
	global_load_lds_dwordx4 v[232:233], off
	s_waitcnt vmcnt(8)
	s_waitcnt lgkmcnt(0)
	s_barrier
	s_setprio 1
	s_waitcnt lgkmcnt(0)
	v_mfma_f32_16x16x32_bf16 v[60:63], v[132:135], v[186:189], v[60:63]
	v_mfma_f32_16x16x32_bf16 v[56:59], v[140:143], v[186:189], v[56:59]
	v_mfma_f32_16x16x32_bf16 v[52:55], v[132:135], v[194:197], v[52:55]
	v_mfma_f32_16x16x32_bf16 v[48:51], v[140:143], v[194:197], v[48:51]
	v_mfma_f32_16x16x32_bf16 v[44:47], v[132:135], v[214:217], v[44:47]
	v_mfma_f32_16x16x32_bf16 v[40:43], v[140:143], v[214:217], v[40:43]
	v_mfma_f32_16x16x32_bf16 v[36:39], v[132:135], v[222:225], v[36:39]
	v_mfma_f32_16x16x32_bf16 v[32:35], v[140:143], v[222:225], v[32:35]
	v_mfma_f32_16x16x32_bf16 v[60:63], v[136:139], v[190:193], v[60:63]
	v_mfma_f32_16x16x32_bf16 v[56:59], v[166:169], v[190:193], v[56:59]
	v_mfma_f32_16x16x32_bf16 v[52:55], v[136:139], v[210:213], v[52:55]
	v_mfma_f32_16x16x32_bf16 v[48:51], v[166:169], v[210:213], v[48:51]
	v_mfma_f32_16x16x32_bf16 v[44:47], v[136:139], v[218:221], v[44:47]
	v_mfma_f32_16x16x32_bf16 v[40:43], v[166:169], v[218:221], v[40:43]
	v_mfma_f32_16x16x32_bf16 v[36:39], v[136:139], v[226:229], v[36:39]
	v_mfma_f32_16x16x32_bf16 v[32:35], v[166:169], v[226:229], v[32:35]
	s_setprio 0
	s_setprio 1
	v_mfma_f32_16x16x32_bf16 v[28:31], v[170:173], v[186:189], v[28:31]
	v_mfma_f32_16x16x32_bf16 v[24:27], v[178:181], v[186:189], v[24:27]
	v_mfma_f32_16x16x32_bf16 v[20:23], v[170:173], v[194:197], v[20:23]
	v_mfma_f32_16x16x32_bf16 v[16:19], v[178:181], v[194:197], v[16:19]
	v_mfma_f32_16x16x32_bf16 v[12:15], v[170:173], v[214:217], v[12:15]
	v_mfma_f32_16x16x32_bf16 v[8:11], v[178:181], v[214:217], v[8:11]
	v_mfma_f32_16x16x32_bf16 v[4:7], v[170:173], v[222:225], v[4:7]
	v_mfma_f32_16x16x32_bf16 v[0:3], v[178:181], v[222:225], v[0:3]
	v_mfma_f32_16x16x32_bf16 v[28:31], v[174:177], v[190:193], v[28:31]
	v_mfma_f32_16x16x32_bf16 v[24:27], v[182:185], v[190:193], v[24:27]
	v_mfma_f32_16x16x32_bf16 v[20:23], v[174:177], v[210:213], v[20:23]
	v_mfma_f32_16x16x32_bf16 v[16:19], v[182:185], v[210:213], v[16:19]
	v_mfma_f32_16x16x32_bf16 v[12:15], v[174:177], v[218:221], v[12:15]
	v_mfma_f32_16x16x32_bf16 v[8:11], v[182:185], v[218:221], v[8:11]
	v_mfma_f32_16x16x32_bf16 v[4:7], v[174:177], v[226:229], v[4:7]
	v_mfma_f32_16x16x32_bf16 v[0:3], v[182:185], v[226:229], v[0:3]
	s_setprio 0
	s_barrier
	s_add_i32 s72, 0, 0x18000
	v_add_u32_e32 v156, s72, v159
	s_add_i32 s73, 0, 0x1c000
	ds_read_b128 v[132:135], v156
	ds_read_b128 v[136:139], v156 offset:1024
	ds_read_b128 v[140:143], v156 offset:2048
	ds_read_b128 v[166:169], v156 offset:3072
	v_add_u32_e32 v156, s73, v159
	ds_read_b128 v[170:173], v156
	ds_read_b128 v[174:177], v156 offset:1024
	ds_read_b128 v[178:181], v156 offset:2048
	ds_read_b128 v[182:185], v156 offset:3072
	s_add_u32 s44, s44, 0x80000
	s_addc_u32 s45, s45, 0
	s_mov_b32 m0, s49
	v_lshl_add_u64 v[248:249], s[44:45], 0, v[144:145]
	ds_read_b128 v[186:189], v165 offset:32768
	ds_read_b128 v[190:193], v165 offset:33792
	ds_read_b128 v[194:197], v165 offset:34816
	ds_read_b128 v[210:213], v165 offset:35840
	ds_read_b128 v[214:217], v165 offset:36864
	ds_read_b128 v[218:221], v165 offset:37888
	ds_read_b128 v[222:225], v165 offset:38912
	ds_read_b128 v[226:229], v165 offset:39936
	global_load_lds_dwordx4 v[248:249], off
	v_lshl_add_u64 v[248:249], s[44:45], 0, v[146:147]
	s_mov_b32 m0, s50
	s_nop 0
	global_load_lds_dwordx4 v[248:249], off
	s_waitcnt vmcnt(8)
	s_waitcnt lgkmcnt(0)
	s_barrier
	s_setprio 1
	s_waitcnt lgkmcnt(0)
	v_mfma_f32_16x16x32_bf16 v[124:127], v[132:135], v[186:189], v[124:127]
	v_mfma_f32_16x16x32_bf16 v[120:123], v[140:143], v[186:189], v[120:123]
	v_mfma_f32_16x16x32_bf16 v[116:119], v[132:135], v[194:197], v[116:119]
	v_mfma_f32_16x16x32_bf16 v[112:115], v[140:143], v[194:197], v[112:115]
	v_mfma_f32_16x16x32_bf16 v[108:111], v[132:135], v[214:217], v[108:111]
	v_mfma_f32_16x16x32_bf16 v[104:107], v[140:143], v[214:217], v[104:107]
	v_mfma_f32_16x16x32_bf16 v[100:103], v[132:135], v[222:225], v[100:103]
	v_mfma_f32_16x16x32_bf16 v[96:99], v[140:143], v[222:225], v[96:99]
	v_mfma_f32_16x16x32_bf16 v[124:127], v[136:139], v[190:193], v[124:127]
	v_mfma_f32_16x16x32_bf16 v[120:123], v[166:169], v[190:193], v[120:123]
	v_mfma_f32_16x16x32_bf16 v[116:119], v[136:139], v[210:213], v[116:119]
	v_mfma_f32_16x16x32_bf16 v[112:115], v[166:169], v[210:213], v[112:115]
	v_mfma_f32_16x16x32_bf16 v[108:111], v[136:139], v[218:221], v[108:111]
	v_mfma_f32_16x16x32_bf16 v[104:107], v[166:169], v[218:221], v[104:107]
	v_mfma_f32_16x16x32_bf16 v[100:103], v[136:139], v[226:229], v[100:103]
	v_mfma_f32_16x16x32_bf16 v[96:99], v[166:169], v[226:229], v[96:99]
	s_setprio 0
	s_setprio 1
	v_mfma_f32_16x16x32_bf16 v[92:95], v[170:173], v[186:189], v[92:95]
	v_mfma_f32_16x16x32_bf16 v[88:91], v[178:181], v[186:189], v[88:91]
	v_mfma_f32_16x16x32_bf16 v[84:87], v[170:173], v[194:197], v[84:87]
	v_mfma_f32_16x16x32_bf16 v[80:83], v[178:181], v[194:197], v[80:83]
	v_mfma_f32_16x16x32_bf16 v[76:79], v[170:173], v[214:217], v[76:79]
	v_mfma_f32_16x16x32_bf16 v[72:75], v[178:181], v[214:217], v[72:75]
	v_mfma_f32_16x16x32_bf16 v[68:71], v[170:173], v[222:225], v[68:71]
	v_mfma_f32_16x16x32_bf16 v[64:67], v[178:181], v[222:225], v[64:67]
	v_mfma_f32_16x16x32_bf16 v[92:95], v[174:177], v[190:193], v[92:95]
	v_mfma_f32_16x16x32_bf16 v[88:91], v[182:185], v[190:193], v[88:91]
	v_mfma_f32_16x16x32_bf16 v[84:87], v[174:177], v[210:213], v[84:87]
	v_mfma_f32_16x16x32_bf16 v[80:83], v[182:185], v[210:213], v[80:83]
	v_mfma_f32_16x16x32_bf16 v[76:79], v[174:177], v[218:221], v[76:79]
	v_mfma_f32_16x16x32_bf16 v[72:75], v[182:185], v[218:221], v[72:75]
	v_mfma_f32_16x16x32_bf16 v[68:71], v[174:177], v[226:229], v[68:71]
	v_mfma_f32_16x16x32_bf16 v[64:67], v[182:185], v[226:229], v[64:67]
	s_setprio 0
	s_barrier
	s_add_i32 s44, s72, s29
	v_lshl_add_u64 v[154:155], v[154:155], 0, s[12:13]
	s_mov_b32 m0, s44
	ds_read_b128 v[186:189], v165 offset:49152
	ds_read_b128 v[190:193], v165 offset:50176
	ds_read_b128 v[194:197], v165 offset:51200
	ds_read_b128 v[210:213], v165 offset:52224
	ds_read_b128 v[214:217], v165 offset:53248
	ds_read_b128 v[218:221], v165 offset:54272
	ds_read_b128 v[222:225], v165 offset:55296
	ds_read_b128 v[226:229], v165 offset:56320
	global_load_lds_dwordx4 v[154:155], off
	s_add_i32 m0, s44, 0x2000
	s_add_u32 s36, s36, 0x80080
	v_lshl_add_u64 v[154:155], v[198:199], 0, s[12:13]
	s_addc_u32 s37, s37, 0
	s_add_i32 s44, s73, s29
	global_load_lds_dwordx4 v[154:155], off
	v_lshl_add_u64 v[154:155], s[36:37], 0, v[204:205]
	s_mov_b32 m0, s44
	s_nop 0
	global_load_lds_dwordx4 v[154:155], off
	v_lshl_add_u64 v[154:155], s[36:37], 0, v[148:149]
	s_add_i32 m0, s44, 0x2000
	s_nop 0
	global_load_lds_dwordx4 v[154:155], off
	v_lshl_add_u64 v[154:155], v[230:231], 0, s[12:13]
	s_mov_b32 m0, s54
	s_nop 0
	global_load_lds_dwordx4 v[154:155], off
	v_lshl_add_u64 v[154:155], v[232:233], 0, s[12:13]
	s_mov_b32 m0, s55
	s_nop 0
	global_load_lds_dwordx4 v[154:155], off
	s_waitcnt vmcnt(8)
	s_waitcnt lgkmcnt(0)
	s_barrier
	s_setprio 1
	s_waitcnt lgkmcnt(0)
	v_mfma_f32_16x16x32_bf16 v[60:63], v[132:135], v[186:189], v[60:63]
	v_mfma_f32_16x16x32_bf16 v[56:59], v[140:143], v[186:189], v[56:59]
	v_mfma_f32_16x16x32_bf16 v[52:55], v[132:135], v[194:197], v[52:55]
	v_mfma_f32_16x16x32_bf16 v[48:51], v[140:143], v[194:197], v[48:51]
	v_mfma_f32_16x16x32_bf16 v[44:47], v[132:135], v[214:217], v[44:47]
	v_mfma_f32_16x16x32_bf16 v[40:43], v[140:143], v[214:217], v[40:43]
	v_mfma_f32_16x16x32_bf16 v[36:39], v[132:135], v[222:225], v[36:39]
	v_mfma_f32_16x16x32_bf16 v[32:35], v[140:143], v[222:225], v[32:35]
	v_mfma_f32_16x16x32_bf16 v[60:63], v[136:139], v[190:193], v[60:63]
	v_mfma_f32_16x16x32_bf16 v[56:59], v[166:169], v[190:193], v[56:59]
	v_mfma_f32_16x16x32_bf16 v[52:55], v[136:139], v[210:213], v[52:55]
	v_mfma_f32_16x16x32_bf16 v[48:51], v[166:169], v[210:213], v[48:51]
	v_mfma_f32_16x16x32_bf16 v[44:47], v[136:139], v[218:221], v[44:47]
	v_mfma_f32_16x16x32_bf16 v[40:43], v[166:169], v[218:221], v[40:43]
	v_mfma_f32_16x16x32_bf16 v[36:39], v[136:139], v[226:229], v[36:39]
	v_mfma_f32_16x16x32_bf16 v[32:35], v[166:169], v[226:229], v[32:35]
	s_setprio 0
	s_setprio 1
	v_mfma_f32_16x16x32_bf16 v[28:31], v[170:173], v[186:189], v[28:31]
	v_mfma_f32_16x16x32_bf16 v[24:27], v[178:181], v[186:189], v[24:27]
	v_mfma_f32_16x16x32_bf16 v[20:23], v[170:173], v[194:197], v[20:23]
	v_mfma_f32_16x16x32_bf16 v[16:19], v[178:181], v[194:197], v[16:19]
	v_mfma_f32_16x16x32_bf16 v[12:15], v[170:173], v[214:217], v[12:15]
	v_mfma_f32_16x16x32_bf16 v[8:11], v[178:181], v[214:217], v[8:11]
	v_mfma_f32_16x16x32_bf16 v[4:7], v[170:173], v[222:225], v[4:7]
	v_mfma_f32_16x16x32_bf16 v[0:3], v[178:181], v[222:225], v[0:3]
	v_mfma_f32_16x16x32_bf16 v[28:31], v[174:177], v[190:193], v[28:31]
	v_mfma_f32_16x16x32_bf16 v[24:27], v[182:185], v[190:193], v[24:27]
	v_mfma_f32_16x16x32_bf16 v[20:23], v[174:177], v[210:213], v[20:23]
	v_mfma_f32_16x16x32_bf16 v[16:19], v[182:185], v[210:213], v[16:19]
	v_mfma_f32_16x16x32_bf16 v[12:15], v[174:177], v[218:221], v[12:15]
	v_mfma_f32_16x16x32_bf16 v[8:11], v[182:185], v[218:221], v[8:11]
	v_mfma_f32_16x16x32_bf16 v[4:7], v[174:177], v[226:229], v[4:7]
	v_mfma_f32_16x16x32_bf16 v[0:3], v[182:185], v[226:229], v[0:3]
	s_setprio 0
	s_barrier
	s_add_i32 s71, s71, 2
	s_add_u32 s0, s0, 0x100
	s_addc_u32 s1, s1, 0
	s_cmp_gt_u32 s71, 29
	s_cbranch_scc0 .LBB0_318
.Lpeel_exit_318:
	s_and_b64 vcc, exec, s[20:21]
	s_cbranch_vccz .LBB0_321
	s_barrier

.LBB0_353:
	v_bfe_u32 v9, v99, 4, 2
	v_and_b32_e32 v8, 15, v99
	v_lshlrev_b32_e32 v11, 4, v9
	v_lshl_or_b32 v153, s7, 6, v8
	v_lshl_or_b32 v11, v8, 6, v11
	v_lshlrev_b32_e32 v8, 2, v8
	s_and_b32 s45, s6, 3
	s_lshl_b32 s6, s7, 13
	v_and_b32_e32 v12, 32, v8
	s_add_i32 m0, s41, 0x18000
	v_lshl_add_u64 v[2:3], v[2:3], 0, s[12:13]
	v_bitop3_b32 v13, v11, s6, v12 bitop3:0xde
	s_lshl_b32 s6, s45, 12
	s_waitcnt vmcnt(2)
	s_barrier
	global_load_lds_dwordx4 v[2:3], off
	v_lshl_add_u64 v[2:3], v[4:5], 0, s[12:13]
	s_add_i32 m0, s41, 0x1a000
	s_add_i32 s46, s41, 0x8000
	s_add_i32 s47, s41, 0xa000
	v_bitop3_b32 v154, v11, s6, v12 bitop3:0xde
	global_load_lds_dwordx4 v[2:3], off
	v_lshl_add_u64 v[0:1], v[0:1], 0, s[12:13]
	s_mov_b32 m0, s46
	s_add_u32 s6, s0, 0x80080
	global_load_lds_dwordx4 v[0:1], off
	v_lshl_add_u64 v[0:1], v[6:7], 0, s[12:13]
	s_mov_b32 m0, s47
	s_addc_u32 s7, s1, 0
	global_load_lds_dwordx4 v[0:1], off
	s_add_i32 m0, s41, 0x1c000
	v_lshl_add_u64 v[0:1], s[6:7], 0, v[204:205]
	global_load_lds_dwordx4 v[0:1], off
	v_lshl_add_u64 v[0:1], s[6:7], 0, v[128:129]
	s_add_i32 m0, s41, 0x1e000
	v_cmp_lt_i32_e32 vcc, v243, v238
	global_load_lds_dwordx4 v[0:1], off
	s_nop 0
	v_cndmask_b32_e32 v0, v237, v243, vcc
	v_cmp_lt_i32_e32 vcc, v244, v238
	v_lshlrev_b32_e32 v157, 2, v0
	v_and_b32_e32 v1, 1, v101
	v_cndmask_b32_e32 v0, v237, v244, vcc
	v_lshlrev_b32_e32 v158, 2, v0
	v_lshlrev_b32_e32 v0, 15, v101
	v_and_b32_e32 v0, 0xffff0000, v0
	v_lshl_add_u32 v0, v100, 12, v0
	v_lshl_or_b32 v0, v1, 6, v0
	v_lshl_add_u32 v134, v102, 1, v0
	v_lshlrev_b32_e32 v0, 15, v96
	s_cmpk_lt_u32 s8, 0x100
	v_and_b32_e32 v0, 0xffff0000, v0
	s_cselect_b64 s[6:7], -1, 0
	s_and_b32 s8, s8, 0xffffff00
	v_lshl_add_u32 v0, v97, 12, v0
	v_and_b32_e32 v1, 1, v96
	s_waitcnt vmcnt(6)
	s_add_i32 s8, s8, 0
	v_lshl_or_b32 v0, v1, 6, v0
	v_lshlrev_b32_e32 v10, 3, v9
	s_add_i32 s8, s8, 0x20000
	v_lshl_add_u32 v136, v98, 1, v0
	v_lshl_or_b32 v155, s45, 5, v10
	s_mov_b32 s48, 0
	v_cmp_eq_u32_e64 s[60:61], 0, v9
	v_add_u32_e32 v156, s8, v8
	v_mov_b32_e32 v135, v205
	v_mov_b32_e32 v137, v205
	v_add_u32_e32 v159, 0, v13
	v_readlane_b32 s49, v253, 45
	s_mov_b32 s50, s14
	s_mov_b32 s52, 0
	s_barrier
	s_branch .LBB0_355
.LBB0_354:
	s_mov_b32 s49, s8
	s_mov_b32 s50, s10
	s_mov_b32 s48, s51
	s_mov_b64 s[2:3], s[20:21]
	s_mov_b32 s52, s53
	s_andn2_b64 vcc, exec, s[62:63]
	s_mov_b64 s[0:1], s[14:15]
	s_cbranch_vccz .LBB0_401

.LBB0_361:
	s_add_u32 s54, s0, 0x100
	s_addc_u32 s55, s1, 0
	s_ashr_i32 s11, s10, 31
	s_lshl_b64 s[14:15], s[10:11], 20
	s_add_u32 s20, s16, s14
	s_addc_u32 s21, s17, s15
	s_and_b64 s[14:15], s[64:65], exec
	s_cselect_b32 s11, s21, s3
	s_cselect_b32 s22, s20, s2
	s_ashr_i32 s9, s8, 31
	s_lshl_b64 s[14:15], s[8:9], 20
	s_add_u32 s14, s39, s14
	s_addc_u32 s15, s40, s15
	s_and_b64 s[28:29], s[64:65], exec
	s_cselect_b32 s9, s15, s1
	s_cselect_b32 s25, s14, s0
	s_add_u32 s0, s2, 0x80080
	s_addc_u32 s1, s3, 0
	v_lshl_add_u64 v[138:139], s[0:1], 0, v[134:135]
	s_waitcnt lgkmcnt(0)
	v_lshl_add_u64 v[140:141], s[0:1], 0, v[136:137]
	s_mov_b32 s28, -2
	s_mov_b64 s[0:1], 0
	s_add_u32 s29, s2, s0
	s_addc_u32 s34, s3, s1
	s_add_u32 s29, s29, 0x100
	s_addc_u32 s34, s34, 0
	s_add_u32 s56, s54, s0
	s_addc_u32 s35, s55, s1
	s_add_i32 s57, 0, 0x10000
	s_cmpk_eq_i32 s0, 0xf00
	s_cselect_b32 s37, s11, s34
	s_cselect_b32 s36, s22, s29
	v_add_u32_e32 v150, s57, v154
	s_cselect_b32 s35, s9, s35
	s_cselect_b32 s34, s25, s56
	s_add_i32 s29, 0, 0x14000
	ds_read_b128 v[142:145], v150
	ds_read_b128 v[146:149], v150 offset:1024
	ds_read_b128 v[160:163], v150 offset:2048
	ds_read_b128 v[164:167], v150 offset:3072
	v_add_u32_e32 v150, s29, v154
	ds_read_b128 v[168:171], v150
	ds_read_b128 v[172:175], v150 offset:1024
	ds_read_b128 v[176:179], v150 offset:2048
	ds_read_b128 v[180:183], v150 offset:3072
	v_lshl_add_u64 v[150:151], v[138:139], 0, s[0:1]
	s_add_i32 m0, s41, 0xc000
	ds_read_b128 v[184:187], v159
	ds_read_b128 v[188:191], v159 offset:1024
	ds_read_b128 v[192:195], v159 offset:2048
	ds_read_b128 v[196:199], v159 offset:3072
	ds_read_b128 v[210:213], v159 offset:4096
	ds_read_b128 v[214:217], v159 offset:5120
	ds_read_b128 v[218:221], v159 offset:6144
	ds_read_b128 v[222:225], v159 offset:7168
	global_load_lds_dwordx4 v[150:151], off
	v_lshl_add_u64 v[150:151], v[140:141], 0, s[0:1]
	s_add_i32 m0, s41, 0xe000
	s_nop 0
	global_load_lds_dwordx4 v[150:151], off
	s_waitcnt vmcnt(8)
	s_waitcnt lgkmcnt(0)
	s_barrier
	s_setprio 1
	s_waitcnt lgkmcnt(0)
	v_mfma_f32_16x16x32_bf16 v[124:127], v[142:145], v[184:187], 0
	v_mfma_f32_16x16x32_bf16 v[120:123], v[160:163], v[184:187], 0
	v_mfma_f32_16x16x32_bf16 v[116:119], v[142:145], v[192:195], 0
	v_mfma_f32_16x16x32_bf16 v[112:115], v[160:163], v[192:195], 0
	v_mfma_f32_16x16x32_bf16 v[108:111], v[142:145], v[210:213], 0
	v_mfma_f32_16x16x32_bf16 v[104:107], v[160:163], v[210:213], 0
	v_mfma_f32_16x16x32_bf16 v[100:103], v[142:145], v[218:221], 0
	v_mfma_f32_16x16x32_bf16 v[96:99], v[160:163], v[218:221], 0
	v_mfma_f32_16x16x32_bf16 v[124:127], v[146:149], v[188:191], v[124:127]
	v_mfma_f32_16x16x32_bf16 v[120:123], v[164:167], v[188:191], v[120:123]
	v_mfma_f32_16x16x32_bf16 v[116:119], v[146:149], v[196:199], v[116:119]
	v_mfma_f32_16x16x32_bf16 v[112:115], v[164:167], v[196:199], v[112:115]
	v_mfma_f32_16x16x32_bf16 v[108:111], v[146:149], v[214:217], v[108:111]
	v_mfma_f32_16x16x32_bf16 v[104:107], v[164:167], v[214:217], v[104:107]
	v_mfma_f32_16x16x32_bf16 v[100:103], v[146:149], v[222:225], v[100:103]
	v_mfma_f32_16x16x32_bf16 v[96:99], v[164:167], v[222:225], v[96:99]
	s_setprio 0
	s_setprio 1
	v_mfma_f32_16x16x32_bf16 v[92:95], v[168:171], v[184:187], 0
	v_mfma_f32_16x16x32_bf16 v[88:91], v[176:179], v[184:187], 0
	v_mfma_f32_16x16x32_bf16 v[84:87], v[168:171], v[192:195], 0
	v_mfma_f32_16x16x32_bf16 v[80:83], v[176:179], v[192:195], 0
	v_mfma_f32_16x16x32_bf16 v[76:79], v[168:171], v[210:213], 0
	v_mfma_f32_16x16x32_bf16 v[72:75], v[176:179], v[210:213], 0
	v_mfma_f32_16x16x32_bf16 v[68:71], v[168:171], v[218:221], 0
	v_mfma_f32_16x16x32_bf16 v[64:67], v[176:179], v[218:221], 0
	v_mfma_f32_16x16x32_bf16 v[92:95], v[172:175], v[188:191], v[92:95]
	v_mfma_f32_16x16x32_bf16 v[88:91], v[180:183], v[188:191], v[88:91]
	v_mfma_f32_16x16x32_bf16 v[84:87], v[172:175], v[196:199], v[84:87]
	v_mfma_f32_16x16x32_bf16 v[80:83], v[180:183], v[196:199], v[80:83]
	v_mfma_f32_16x16x32_bf16 v[76:79], v[172:175], v[214:217], v[76:79]
	v_mfma_f32_16x16x32_bf16 v[72:75], v[180:183], v[214:217], v[72:75]
	v_mfma_f32_16x16x32_bf16 v[68:71], v[172:175], v[222:225], v[68:71]
	v_mfma_f32_16x16x32_bf16 v[64:67], v[180:183], v[222:225], v[64:67]
	s_setprio 0
	s_barrier
	s_add_i32 s56, s57, s38
	v_lshl_add_u64 v[150:151], s[34:35], 0, v[204:205]
	s_mov_b32 m0, s56
	ds_read_b128 v[184:187], v159 offset:16384
	ds_read_b128 v[188:191], v159 offset:17408
	ds_read_b128 v[192:195], v159 offset:18432
	ds_read_b128 v[196:199], v159 offset:19456
	ds_read_b128 v[210:213], v159 offset:20480
	ds_read_b128 v[214:217], v159 offset:21504
	ds_read_b128 v[218:221], v159 offset:22528
	ds_read_b128 v[222:225], v159 offset:23552
	global_load_lds_dwordx4 v[150:151], off
	s_add_i32 m0, s56, 0x2000
	s_add_u32 s56, s34, 0x80000
	v_lshl_add_u64 v[226:227], s[34:35], 0, v[128:129]
	s_addc_u32 s57, s35, 0
	s_add_i32 s29, s29, s38
	global_load_lds_dwordx4 v[226:227], off
	v_lshl_add_u64 v[228:229], s[56:57], 0, v[204:205]
	s_mov_b32 m0, s29
	v_lshl_add_u64 v[230:231], s[36:37], 0, v[130:131]
	global_load_lds_dwordx4 v[228:229], off
	v_lshl_add_u64 v[228:229], s[56:57], 0, v[128:129]
	s_add_i32 m0, s29, 0x2000
	s_nop 0
	global_load_lds_dwordx4 v[228:229], off
	v_lshl_add_u64 v[228:229], s[36:37], 0, v[132:133]
	s_mov_b32 m0, s41
	s_nop 0
	global_load_lds_dwordx4 v[228:229], off
	s_mov_b32 m0, s42
	s_nop 0
	global_load_lds_dwordx4 v[230:231], off
	s_waitcnt vmcnt(8)
	s_waitcnt lgkmcnt(0)
	s_barrier
	s_setprio 1
	s_waitcnt lgkmcnt(0)
	v_mfma_f32_16x16x32_bf16 v[60:63], v[142:145], v[184:187], 0
	v_mfma_f32_16x16x32_bf16 v[56:59], v[160:163], v[184:187], 0
	v_mfma_f32_16x16x32_bf16 v[52:55], v[142:145], v[192:195], 0
	v_mfma_f32_16x16x32_bf16 v[48:51], v[160:163], v[192:195], 0
	v_mfma_f32_16x16x32_bf16 v[44:47], v[142:145], v[210:213], 0
	v_mfma_f32_16x16x32_bf16 v[40:43], v[160:163], v[210:213], 0
	v_mfma_f32_16x16x32_bf16 v[36:39], v[142:145], v[218:221], 0
	v_mfma_f32_16x16x32_bf16 v[32:35], v[160:163], v[218:221], 0
	v_mfma_f32_16x16x32_bf16 v[60:63], v[146:149], v[188:191], v[60:63]
	v_mfma_f32_16x16x32_bf16 v[56:59], v[164:167], v[188:191], v[56:59]
	v_mfma_f32_16x16x32_bf16 v[52:55], v[146:149], v[196:199], v[52:55]
	v_mfma_f32_16x16x32_bf16 v[48:51], v[164:167], v[196:199], v[48:51]
	v_mfma_f32_16x16x32_bf16 v[44:47], v[146:149], v[214:217], v[44:47]
	v_mfma_f32_16x16x32_bf16 v[40:43], v[164:167], v[214:217], v[40:43]
	v_mfma_f32_16x16x32_bf16 v[36:39], v[146:149], v[222:225], v[36:39]
	v_mfma_f32_16x16x32_bf16 v[32:35], v[164:167], v[222:225], v[32:35]
	s_setprio 0
	s_setprio 1
	v_mfma_f32_16x16x32_bf16 v[28:31], v[168:171], v[184:187], 0
	v_mfma_f32_16x16x32_bf16 v[24:27], v[176:179], v[184:187], 0
	v_mfma_f32_16x16x32_bf16 v[20:23], v[168:171], v[192:195], 0
	v_mfma_f32_16x16x32_bf16 v[16:19], v[176:179], v[192:195], 0
	v_mfma_f32_16x16x32_bf16 v[12:15], v[168:171], v[210:213], 0
	v_mfma_f32_16x16x32_bf16 v[8:11], v[176:179], v[210:213], 0
	v_mfma_f32_16x16x32_bf16 v[4:7], v[168:171], v[218:221], 0
	v_mfma_f32_16x16x32_bf16 v[0:3], v[176:179], v[218:221], 0
	v_mfma_f32_16x16x32_bf16 v[28:31], v[172:175], v[188:191], v[28:31]
	v_mfma_f32_16x16x32_bf16 v[24:27], v[180:183], v[188:191], v[24:27]
	v_mfma_f32_16x16x32_bf16 v[20:23], v[172:175], v[196:199], v[20:23]
	v_mfma_f32_16x16x32_bf16 v[16:19], v[180:183], v[196:199], v[16:19]
	v_mfma_f32_16x16x32_bf16 v[12:15], v[172:175], v[214:217], v[12:15]
	v_mfma_f32_16x16x32_bf16 v[8:11], v[180:183], v[214:217], v[8:11]
	v_mfma_f32_16x16x32_bf16 v[4:7], v[172:175], v[222:225], v[4:7]
	v_mfma_f32_16x16x32_bf16 v[0:3], v[180:183], v[222:225], v[0:3]
	s_setprio 0
	s_barrier
	s_add_i32 s29, 0, 0x18000
	v_add_u32_e32 v152, s29, v154
	s_add_i32 s56, 0, 0x1c000
	ds_read_b128 v[142:145], v152
	ds_read_b128 v[146:149], v152 offset:1024
	ds_read_b128 v[160:163], v152 offset:2048
	ds_read_b128 v[164:167], v152 offset:3072
	v_add_u32_e32 v152, s56, v154
	ds_read_b128 v[168:171], v152
	ds_read_b128 v[172:175], v152 offset:1024
	ds_read_b128 v[176:179], v152 offset:2048
	ds_read_b128 v[180:183], v152 offset:3072
	s_add_u32 s36, s36, 0x80000
	s_addc_u32 s37, s37, 0
	s_mov_b32 m0, s43
	v_lshl_add_u64 v[232:233], s[36:37], 0, v[132:133]
	ds_read_b128 v[184:187], v159 offset:32768
	ds_read_b128 v[188:191], v159 offset:33792
	ds_read_b128 v[192:195], v159 offset:34816
	ds_read_b128 v[196:199], v159 offset:35840
	ds_read_b128 v[210:213], v159 offset:36864
	ds_read_b128 v[214:217], v159 offset:37888
	ds_read_b128 v[218:221], v159 offset:38912
	ds_read_b128 v[222:225], v159 offset:39936
	global_load_lds_dwordx4 v[232:233], off
	v_lshl_add_u64 v[232:233], s[36:37], 0, v[130:131]
	s_mov_b32 m0, s44
	s_nop 0
	global_load_lds_dwordx4 v[232:233], off
	s_waitcnt vmcnt(8)
	s_waitcnt lgkmcnt(0)
	s_barrier
	s_setprio 1
	s_waitcnt lgkmcnt(0)
	v_mfma_f32_16x16x32_bf16 v[124:127], v[142:145], v[184:187], v[124:127]
	v_mfma_f32_16x16x32_bf16 v[120:123], v[160:163], v[184:187], v[120:123]
	v_mfma_f32_16x16x32_bf16 v[116:119], v[142:145], v[192:195], v[116:119]
	v_mfma_f32_16x16x32_bf16 v[112:115], v[160:163], v[192:195], v[112:115]
	v_mfma_f32_16x16x32_bf16 v[108:111], v[142:145], v[210:213], v[108:111]
	v_mfma_f32_16x16x32_bf16 v[104:107], v[160:163], v[210:213], v[104:107]
	v_mfma_f32_16x16x32_bf16 v[100:103], v[142:145], v[218:221], v[100:103]
	v_mfma_f32_16x16x32_bf16 v[96:99], v[160:163], v[218:221], v[96:99]
	v_mfma_f32_16x16x32_bf16 v[124:127], v[146:149], v[188:191], v[124:127]
	v_mfma_f32_16x16x32_bf16 v[120:123], v[164:167], v[188:191], v[120:123]
	v_mfma_f32_16x16x32_bf16 v[116:119], v[146:149], v[196:199], v[116:119]
	v_mfma_f32_16x16x32_bf16 v[112:115], v[164:167], v[196:199], v[112:115]
	v_mfma_f32_16x16x32_bf16 v[108:111], v[146:149], v[214:217], v[108:111]
	v_mfma_f32_16x16x32_bf16 v[104:107], v[164:167], v[214:217], v[104:107]
	v_mfma_f32_16x16x32_bf16 v[100:103], v[146:149], v[222:225], v[100:103]
	v_mfma_f32_16x16x32_bf16 v[96:99], v[164:167], v[222:225], v[96:99]
	s_setprio 0
	s_setprio 1
	v_mfma_f32_16x16x32_bf16 v[92:95], v[168:171], v[184:187], v[92:95]
	v_mfma_f32_16x16x32_bf16 v[88:91], v[176:179], v[184:187], v[88:91]
	v_mfma_f32_16x16x32_bf16 v[84:87], v[168:171], v[192:195], v[84:87]
	v_mfma_f32_16x16x32_bf16 v[80:83], v[176:179], v[192:195], v[80:83]
	v_mfma_f32_16x16x32_bf16 v[76:79], v[168:171], v[210:213], v[76:79]
	v_mfma_f32_16x16x32_bf16 v[72:75], v[176:179], v[210:213], v[72:75]
	v_mfma_f32_16x16x32_bf16 v[68:71], v[168:171], v[218:221], v[68:71]
	v_mfma_f32_16x16x32_bf16 v[64:67], v[176:179], v[218:221], v[64:67]
	v_mfma_f32_16x16x32_bf16 v[92:95], v[172:175], v[188:191], v[92:95]
	v_mfma_f32_16x16x32_bf16 v[88:91], v[180:183], v[188:191], v[88:91]
	v_mfma_f32_16x16x32_bf16 v[84:87], v[172:175], v[196:199], v[84:87]
	v_mfma_f32_16x16x32_bf16 v[80:83], v[180:183], v[196:199], v[80:83]
	v_mfma_f32_16x16x32_bf16 v[76:79], v[172:175], v[214:217], v[76:79]
	v_mfma_f32_16x16x32_bf16 v[72:75], v[180:183], v[214:217], v[72:75]
	v_mfma_f32_16x16x32_bf16 v[68:71], v[172:175], v[222:225], v[68:71]
	v_mfma_f32_16x16x32_bf16 v[64:67], v[180:183], v[222:225], v[64:67]
	s_setprio 0
	s_barrier
	s_add_i32 s29, s29, s38
	v_lshl_add_u64 v[150:151], v[150:151], 0, s[12:13]
	s_mov_b32 m0, s29
	ds_read_b128 v[184:187], v159 offset:49152
	ds_read_b128 v[188:191], v159 offset:50176
	ds_read_b128 v[192:195], v159 offset:51200
	ds_read_b128 v[196:199], v159 offset:52224
	ds_read_b128 v[210:213], v159 offset:53248
	ds_read_b128 v[214:217], v159 offset:54272
	ds_read_b128 v[218:221], v159 offset:55296
	ds_read_b128 v[222:225], v159 offset:56320
	global_load_lds_dwordx4 v[150:151], off
	s_add_i32 m0, s29, 0x2000
	s_add_u32 s34, s34, 0x80080
	v_lshl_add_u64 v[150:151], v[226:227], 0, s[12:13]
	s_addc_u32 s35, s35, 0
	s_add_i32 s29, s56, s38
	global_load_lds_dwordx4 v[150:151], off
	v_lshl_add_u64 v[150:151], s[34:35], 0, v[204:205]
	s_mov_b32 m0, s29
	s_nop 0
	global_load_lds_dwordx4 v[150:151], off
	v_lshl_add_u64 v[150:151], s[34:35], 0, v[128:129]
	s_add_i32 m0, s29, 0x2000
	s_nop 0
	global_load_lds_dwordx4 v[150:151], off
	v_lshl_add_u64 v[150:151], v[228:229], 0, s[12:13]
	s_mov_b32 m0, s46
	s_nop 0
	global_load_lds_dwordx4 v[150:151], off
	v_lshl_add_u64 v[150:151], v[230:231], 0, s[12:13]
	s_mov_b32 m0, s47
	s_nop 0
	global_load_lds_dwordx4 v[150:151], off
	s_waitcnt vmcnt(8)
	s_waitcnt lgkmcnt(0)
	s_barrier
	s_setprio 1
	s_waitcnt lgkmcnt(0)
	v_mfma_f32_16x16x32_bf16 v[60:63], v[142:145], v[184:187], v[60:63]
	v_mfma_f32_16x16x32_bf16 v[56:59], v[160:163], v[184:187], v[56:59]
	v_mfma_f32_16x16x32_bf16 v[52:55], v[142:145], v[192:195], v[52:55]
	v_mfma_f32_16x16x32_bf16 v[48:51], v[160:163], v[192:195], v[48:51]
	v_mfma_f32_16x16x32_bf16 v[44:47], v[142:145], v[210:213], v[44:47]
	v_mfma_f32_16x16x32_bf16 v[40:43], v[160:163], v[210:213], v[40:43]
	v_mfma_f32_16x16x32_bf16 v[36:39], v[142:145], v[218:221], v[36:39]
	v_mfma_f32_16x16x32_bf16 v[32:35], v[160:163], v[218:221], v[32:35]
	v_mfma_f32_16x16x32_bf16 v[60:63], v[146:149], v[188:191], v[60:63]
	v_mfma_f32_16x16x32_bf16 v[56:59], v[164:167], v[188:191], v[56:59]
	v_mfma_f32_16x16x32_bf16 v[52:55], v[146:149], v[196:199], v[52:55]
	v_mfma_f32_16x16x32_bf16 v[48:51], v[164:167], v[196:199], v[48:51]
	v_mfma_f32_16x16x32_bf16 v[44:47], v[146:149], v[214:217], v[44:47]
	v_mfma_f32_16x16x32_bf16 v[40:43], v[164:167], v[214:217], v[40:43]
	v_mfma_f32_16x16x32_bf16 v[36:39], v[146:149], v[222:225], v[36:39]
	v_mfma_f32_16x16x32_bf16 v[32:35], v[164:167], v[222:225], v[32:35]
	s_setprio 0
	s_setprio 1
	v_mfma_f32_16x16x32_bf16 v[28:31], v[168:171], v[184:187], v[28:31]
	v_mfma_f32_16x16x32_bf16 v[24:27], v[176:179], v[184:187], v[24:27]
	v_mfma_f32_16x16x32_bf16 v[20:23], v[168:171], v[192:195], v[20:23]
	v_mfma_f32_16x16x32_bf16 v[16:19], v[176:179], v[192:195], v[16:19]
	v_mfma_f32_16x16x32_bf16 v[12:15], v[168:171], v[210:213], v[12:15]
	v_mfma_f32_16x16x32_bf16 v[8:11], v[176:179], v[210:213], v[8:11]
	v_mfma_f32_16x16x32_bf16 v[4:7], v[168:171], v[218:221], v[4:7]
	v_mfma_f32_16x16x32_bf16 v[0:3], v[176:179], v[218:221], v[0:3]
	v_mfma_f32_16x16x32_bf16 v[28:31], v[172:175], v[188:191], v[28:31]
	v_mfma_f32_16x16x32_bf16 v[24:27], v[180:183], v[188:191], v[24:27]
	v_mfma_f32_16x16x32_bf16 v[20:23], v[172:175], v[196:199], v[20:23]
	v_mfma_f32_16x16x32_bf16 v[16:19], v[180:183], v[196:199], v[16:19]
	v_mfma_f32_16x16x32_bf16 v[12:15], v[172:175], v[214:217], v[12:15]
	v_mfma_f32_16x16x32_bf16 v[8:11], v[180:183], v[214:217], v[8:11]
	v_mfma_f32_16x16x32_bf16 v[4:7], v[172:175], v[222:225], v[4:7]
	v_mfma_f32_16x16x32_bf16 v[0:3], v[180:183], v[222:225], v[0:3]
	s_setprio 0
	s_barrier
	s_add_i32 s28, s28, 2
	s_add_u32 s0, s0, 0x100
	s_addc_u32 s1, s1, 0
	s_cmp_gt_u32 s28, 29
	s_cbranch_scc1 .Lpeel_exit_362
.LBB0_362:
	s_add_u32 s29, s2, s0
	s_addc_u32 s34, s3, s1
	s_add_u32 s29, s29, 0x100
	s_addc_u32 s34, s34, 0
	s_add_u32 s56, s54, s0
	s_addc_u32 s35, s55, s1
	s_add_i32 s57, 0, 0x10000
	s_cmpk_eq_i32 s0, 0xf00
	s_cselect_b32 s37, s11, s34
	s_cselect_b32 s36, s22, s29
	v_add_u32_e32 v150, s57, v154
	s_cselect_b32 s35, s9, s35
	s_cselect_b32 s34, s25, s56
	s_add_i32 s29, 0, 0x14000
	ds_read_b128 v[142:145], v150
	ds_read_b128 v[146:149], v150 offset:1024
	ds_read_b128 v[160:163], v150 offset:2048
	ds_read_b128 v[164:167], v150 offset:3072
	v_add_u32_e32 v150, s29, v154
	ds_read_b128 v[168:171], v150
	ds_read_b128 v[172:175], v150 offset:1024
	ds_read_b128 v[176:179], v150 offset:2048
	ds_read_b128 v[180:183], v150 offset:3072
	v_lshl_add_u64 v[150:151], v[138:139], 0, s[0:1]
	s_add_i32 m0, s41, 0xc000
	ds_read_b128 v[184:187], v159
	ds_read_b128 v[188:191], v159 offset:1024
	ds_read_b128 v[192:195], v159 offset:2048
	ds_read_b128 v[196:199], v159 offset:3072
	ds_read_b128 v[210:213], v159 offset:4096
	ds_read_b128 v[214:217], v159 offset:5120
	ds_read_b128 v[218:221], v159 offset:6144
	ds_read_b128 v[222:225], v159 offset:7168
	global_load_lds_dwordx4 v[150:151], off
	v_lshl_add_u64 v[150:151], v[140:141], 0, s[0:1]
	s_add_i32 m0, s41, 0xe000
	s_nop 0
	global_load_lds_dwordx4 v[150:151], off
	s_waitcnt vmcnt(8)
	s_waitcnt lgkmcnt(0)
	s_barrier
	s_setprio 1
	s_waitcnt lgkmcnt(0)
	v_mfma_f32_16x16x32_bf16 v[124:127], v[142:145], v[184:187], v[124:127]
	v_mfma_f32_16x16x32_bf16 v[120:123], v[160:163], v[184:187], v[120:123]
	v_mfma_f32_16x16x32_bf16 v[116:119], v[142:145], v[192:195], v[116:119]
	v_mfma_f32_16x16x32_bf16 v[112:115], v[160:163], v[192:195], v[112:115]
	v_mfma_f32_16x16x32_bf16 v[108:111], v[142:145], v[210:213], v[108:111]
	v_mfma_f32_16x16x32_bf16 v[104:107], v[160:163], v[210:213], v[104:107]
	v_mfma_f32_16x16x32_bf16 v[100:103], v[142:145], v[218:221], v[100:103]
	v_mfma_f32_16x16x32_bf16 v[96:99], v[160:163], v[218:221], v[96:99]
	v_mfma_f32_16x16x32_bf16 v[124:127], v[146:149], v[188:191], v[124:127]
	v_mfma_f32_16x16x32_bf16 v[120:123], v[164:167], v[188:191], v[120:123]
	v_mfma_f32_16x16x32_bf16 v[116:119], v[146:149], v[196:199], v[116:119]
	v_mfma_f32_16x16x32_bf16 v[112:115], v[164:167], v[196:199], v[112:115]
	v_mfma_f32_16x16x32_bf16 v[108:111], v[146:149], v[214:217], v[108:111]
	v_mfma_f32_16x16x32_bf16 v[104:107], v[164:167], v[214:217], v[104:107]
	v_mfma_f32_16x16x32_bf16 v[100:103], v[146:149], v[222:225], v[100:103]
	v_mfma_f32_16x16x32_bf16 v[96:99], v[164:167], v[222:225], v[96:99]
	s_setprio 0
	s_setprio 1
	v_mfma_f32_16x16x32_bf16 v[92:95], v[168:171], v[184:187], v[92:95]
	v_mfma_f32_16x16x32_bf16 v[88:91], v[176:179], v[184:187], v[88:91]
	v_mfma_f32_16x16x32_bf16 v[84:87], v[168:171], v[192:195], v[84:87]
	v_mfma_f32_16x16x32_bf16 v[80:83], v[176:179], v[192:195], v[80:83]
	v_mfma_f32_16x16x32_bf16 v[76:79], v[168:171], v[210:213], v[76:79]
	v_mfma_f32_16x16x32_bf16 v[72:75], v[176:179], v[210:213], v[72:75]
	v_mfma_f32_16x16x32_bf16 v[68:71], v[168:171], v[218:221], v[68:71]
	v_mfma_f32_16x16x32_bf16 v[64:67], v[176:179], v[218:221], v[64:67]
	v_mfma_f32_16x16x32_bf16 v[92:95], v[172:175], v[188:191], v[92:95]
	v_mfma_f32_16x16x32_bf16 v[88:91], v[180:183], v[188:191], v[88:91]
	v_mfma_f32_16x16x32_bf16 v[84:87], v[172:175], v[196:199], v[84:87]
	v_mfma_f32_16x16x32_bf16 v[80:83], v[180:183], v[196:199], v[80:83]
	v_mfma_f32_16x16x32_bf16 v[76:79], v[172:175], v[214:217], v[76:79]
	v_mfma_f32_16x16x32_bf16 v[72:75], v[180:183], v[214:217], v[72:75]
	v_mfma_f32_16x16x32_bf16 v[68:71], v[172:175], v[222:225], v[68:71]
	v_mfma_f32_16x16x32_bf16 v[64:67], v[180:183], v[222:225], v[64:67]
	s_setprio 0
	s_barrier
	s_add_i32 s56, s57, s38
	v_lshl_add_u64 v[150:151], s[34:35], 0, v[204:205]
	s_mov_b32 m0, s56
	ds_read_b128 v[184:187], v159 offset:16384
	ds_read_b128 v[188:191], v159 offset:17408
	ds_read_b128 v[192:195], v159 offset:18432
	ds_read_b128 v[196:199], v159 offset:19456
	ds_read_b128 v[210:213], v159 offset:20480
	ds_read_b128 v[214:217], v159 offset:21504
	ds_read_b128 v[218:221], v159 offset:22528
	ds_read_b128 v[222:225], v159 offset:23552
	global_load_lds_dwordx4 v[150:151], off
	s_add_i32 m0, s56, 0x2000
	s_add_u32 s56, s34, 0x80000
	v_lshl_add_u64 v[226:227], s[34:35], 0, v[128:129]
	s_addc_u32 s57, s35, 0
	s_add_i32 s29, s29, s38
	global_load_lds_dwordx4 v[226:227], off
	v_lshl_add_u64 v[228:229], s[56:57], 0, v[204:205]
	s_mov_b32 m0, s29
	v_lshl_add_u64 v[230:231], s[36:37], 0, v[130:131]
	global_load_lds_dwordx4 v[228:229], off
	v_lshl_add_u64 v[228:229], s[56:57], 0, v[128:129]
	s_add_i32 m0, s29, 0x2000
	s_nop 0
	global_load_lds_dwordx4 v[228:229], off
	v_lshl_add_u64 v[228:229], s[36:37], 0, v[132:133]
	s_mov_b32 m0, s41
	s_nop 0
	global_load_lds_dwordx4 v[228:229], off
	s_mov_b32 m0, s42
	s_nop 0
	global_load_lds_dwordx4 v[230:231], off
	s_waitcnt vmcnt(8)
	s_waitcnt lgkmcnt(0)
	s_barrier
	s_setprio 1
	s_waitcnt lgkmcnt(0)
	v_mfma_f32_16x16x32_bf16 v[60:63], v[142:145], v[184:187], v[60:63]
	v_mfma_f32_16x16x32_bf16 v[56:59], v[160:163], v[184:187], v[56:59]
	v_mfma_f32_16x16x32_bf16 v[52:55], v[142:145], v[192:195], v[52:55]
	v_mfma_f32_16x16x32_bf16 v[48:51], v[160:163], v[192:195], v[48:51]
	v_mfma_f32_16x16x32_bf16 v[44:47], v[142:145], v[210:213], v[44:47]
	v_mfma_f32_16x16x32_bf16 v[40:43], v[160:163], v[210:213], v[40:43]
	v_mfma_f32_16x16x32_bf16 v[36:39], v[142:145], v[218:221], v[36:39]
	v_mfma_f32_16x16x32_bf16 v[32:35], v[160:163], v[218:221], v[32:35]
	v_mfma_f32_16x16x32_bf16 v[60:63], v[146:149], v[188:191], v[60:63]
	v_mfma_f32_16x16x32_bf16 v[56:59], v[164:167], v[188:191], v[56:59]
	v_mfma_f32_16x16x32_bf16 v[52:55], v[146:149], v[196:199], v[52:55]
	v_mfma_f32_16x16x32_bf16 v[48:51], v[164:167], v[196:199], v[48:51]
	v_mfma_f32_16x16x32_bf16 v[44:47], v[146:149], v[214:217], v[44:47]
	v_mfma_f32_16x16x32_bf16 v[40:43], v[164:167], v[214:217], v[40:43]
	v_mfma_f32_16x16x32_bf16 v[36:39], v[146:149], v[222:225], v[36:39]
	v_mfma_f32_16x16x32_bf16 v[32:35], v[164:167], v[222:225], v[32:35]
	s_setprio 0
	s_setprio 1
	v_mfma_f32_16x16x32_bf16 v[28:31], v[168:171], v[184:187], v[28:31]
	v_mfma_f32_16x16x32_bf16 v[24:27], v[176:179], v[184:187], v[24:27]
	v_mfma_f32_16x16x32_bf16 v[20:23], v[168:171], v[192:195], v[20:23]
	v_mfma_f32_16x16x32_bf16 v[16:19], v[176:179], v[192:195], v[16:19]
	v_mfma_f32_16x16x32_bf16 v[12:15], v[168:171], v[210:213], v[12:15]
	v_mfma_f32_16x16x32_bf16 v[8:11], v[176:179], v[210:213], v[8:11]
	v_mfma_f32_16x16x32_bf16 v[4:7], v[168:171], v[218:221], v[4:7]
	v_mfma_f32_16x16x32_bf16 v[0:3], v[176:179], v[218:221], v[0:3]
	v_mfma_f32_16x16x32_bf16 v[28:31], v[172:175], v[188:191], v[28:31]
	v_mfma_f32_16x16x32_bf16 v[24:27], v[180:183], v[188:191], v[24:27]
	v_mfma_f32_16x16x32_bf16 v[20:23], v[172:175], v[196:199], v[20:23]
	v_mfma_f32_16x16x32_bf16 v[16:19], v[180:183], v[196:199], v[16:19]
	v_mfma_f32_16x16x32_bf16 v[12:15], v[172:175], v[214:217], v[12:15]
	v_mfma_f32_16x16x32_bf16 v[8:11], v[180:183], v[214:217], v[8:11]
	v_mfma_f32_16x16x32_bf16 v[4:7], v[172:175], v[222:225], v[4:7]
	v_mfma_f32_16x16x32_bf16 v[0:3], v[180:183], v[222:225], v[0:3]
	s_setprio 0
	s_barrier
	s_add_i32 s29, 0, 0x18000
	v_add_u32_e32 v152, s29, v154
	s_add_i32 s56, 0, 0x1c000
	ds_read_b128 v[142:145], v152
	ds_read_b128 v[146:149], v152 offset:1024
	ds_read_b128 v[160:163], v152 offset:2048
	ds_read_b128 v[164:167], v152 offset:3072
	v_add_u32_e32 v152, s56, v154
	ds_read_b128 v[168:171], v152
	ds_read_b128 v[172:175], v152 offset:1024
	ds_read_b128 v[176:179], v152 offset:2048
	ds_read_b128 v[180:183], v152 offset:3072
	s_add_u32 s36, s36, 0x80000
	s_addc_u32 s37, s37, 0
	s_mov_b32 m0, s43
	v_lshl_add_u64 v[232:233], s[36:37], 0, v[132:133]
	ds_read_b128 v[184:187], v159 offset:32768
	ds_read_b128 v[188:191], v159 offset:33792
	ds_read_b128 v[192:195], v159 offset:34816
	ds_read_b128 v[196:199], v159 offset:35840
	ds_read_b128 v[210:213], v159 offset:36864
	ds_read_b128 v[214:217], v159 offset:37888
	ds_read_b128 v[218:221], v159 offset:38912
	ds_read_b128 v[222:225], v159 offset:39936
	global_load_lds_dwordx4 v[232:233], off
	v_lshl_add_u64 v[232:233], s[36:37], 0, v[130:131]
	s_mov_b32 m0, s44
	s_nop 0
	global_load_lds_dwordx4 v[232:233], off
	s_waitcnt vmcnt(8)
	s_waitcnt lgkmcnt(0)
	s_barrier
	s_setprio 1
	s_waitcnt lgkmcnt(0)
	v_mfma_f32_16x16x32_bf16 v[124:127], v[142:145], v[184:187], v[124:127]
	v_mfma_f32_16x16x32_bf16 v[120:123], v[160:163], v[184:187], v[120:123]
	v_mfma_f32_16x16x32_bf16 v[116:119], v[142:145], v[192:195], v[116:119]
	v_mfma_f32_16x16x32_bf16 v[112:115], v[160:163], v[192:195], v[112:115]
	v_mfma_f32_16x16x32_bf16 v[108:111], v[142:145], v[210:213], v[108:111]
	v_mfma_f32_16x16x32_bf16 v[104:107], v[160:163], v[210:213], v[104:107]
	v_mfma_f32_16x16x32_bf16 v[100:103], v[142:145], v[218:221], v[100:103]
	v_mfma_f32_16x16x32_bf16 v[96:99], v[160:163], v[218:221], v[96:99]
	v_mfma_f32_16x16x32_bf16 v[124:127], v[146:149], v[188:191], v[124:127]
	v_mfma_f32_16x16x32_bf16 v[120:123], v[164:167], v[188:191], v[120:123]
	v_mfma_f32_16x16x32_bf16 v[116:119], v[146:149], v[196:199], v[116:119]
	v_mfma_f32_16x16x32_bf16 v[112:115], v[164:167], v[196:199], v[112:115]
	v_mfma_f32_16x16x32_bf16 v[108:111], v[146:149], v[214:217], v[108:111]
	v_mfma_f32_16x16x32_bf16 v[104:107], v[164:167], v[214:217], v[104:107]
	v_mfma_f32_16x16x32_bf16 v[100:103], v[146:149], v[222:225], v[100:103]
	v_mfma_f32_16x16x32_bf16 v[96:99], v[164:167], v[222:225], v[96:99]
	s_setprio 0
	s_setprio 1
	v_mfma_f32_16x16x32_bf16 v[92:95], v[168:171], v[184:187], v[92:95]
	v_mfma_f32_16x16x32_bf16 v[88:91], v[176:179], v[184:187], v[88:91]
	v_mfma_f32_16x16x32_bf16 v[84:87], v[168:171], v[192:195], v[84:87]
	v_mfma_f32_16x16x32_bf16 v[80:83], v[176:179], v[192:195], v[80:83]
	v_mfma_f32_16x16x32_bf16 v[76:79], v[168:171], v[210:213], v[76:79]
	v_mfma_f32_16x16x32_bf16 v[72:75], v[176:179], v[210:213], v[72:75]
	v_mfma_f32_16x16x32_bf16 v[68:71], v[168:171], v[218:221], v[68:71]
	v_mfma_f32_16x16x32_bf16 v[64:67], v[176:179], v[218:221], v[64:67]
	v_mfma_f32_16x16x32_bf16 v[92:95], v[172:175], v[188:191], v[92:95]
	v_mfma_f32_16x16x32_bf16 v[88:91], v[180:183], v[188:191], v[88:91]
	v_mfma_f32_16x16x32_bf16 v[84:87], v[172:175], v[196:199], v[84:87]
	v_mfma_f32_16x16x32_bf16 v[80:83], v[180:183], v[196:199], v[80:83]
	v_mfma_f32_16x16x32_bf16 v[76:79], v[172:175], v[214:217], v[76:79]
	v_mfma_f32_16x16x32_bf16 v[72:75], v[180:183], v[214:217], v[72:75]
	v_mfma_f32_16x16x32_bf16 v[68:71], v[172:175], v[222:225], v[68:71]
	v_mfma_f32_16x16x32_bf16 v[64:67], v[180:183], v[222:225], v[64:67]
	s_setprio 0
	s_barrier
	s_add_i32 s29, s29, s38
	v_lshl_add_u64 v[150:151], v[150:151], 0, s[12:13]
	s_mov_b32 m0, s29
	ds_read_b128 v[184:187], v159 offset:49152
	ds_read_b128 v[188:191], v159 offset:50176
	ds_read_b128 v[192:195], v159 offset:51200
	ds_read_b128 v[196:199], v159 offset:52224
	ds_read_b128 v[210:213], v159 offset:53248
	ds_read_b128 v[214:217], v159 offset:54272
	ds_read_b128 v[218:221], v159 offset:55296
	ds_read_b128 v[222:225], v159 offset:56320
	global_load_lds_dwordx4 v[150:151], off
	s_add_i32 m0, s29, 0x2000
	s_add_u32 s34, s34, 0x80080
	v_lshl_add_u64 v[150:151], v[226:227], 0, s[12:13]
	s_addc_u32 s35, s35, 0
	s_add_i32 s29, s56, s38
	global_load_lds_dwordx4 v[150:151], off
	v_lshl_add_u64 v[150:151], s[34:35], 0, v[204:205]
	s_mov_b32 m0, s29
	s_nop 0
	global_load_lds_dwordx4 v[150:151], off
	v_lshl_add_u64 v[150:151], s[34:35], 0, v[128:129]
	s_add_i32 m0, s29, 0x2000
	s_nop 0
	global_load_lds_dwordx4 v[150:151], off
	v_lshl_add_u64 v[150:151], v[228:229], 0, s[12:13]
	s_mov_b32 m0, s46
	s_nop 0
	global_load_lds_dwordx4 v[150:151], off
	v_lshl_add_u64 v[150:151], v[230:231], 0, s[12:13]
	s_mov_b32 m0, s47
	s_nop 0
	global_load_lds_dwordx4 v[150:151], off
	s_waitcnt vmcnt(8)
	s_waitcnt lgkmcnt(0)
	s_barrier
	s_setprio 1
	s_waitcnt lgkmcnt(0)
	v_mfma_f32_16x16x32_bf16 v[60:63], v[142:145], v[184:187], v[60:63]
	v_mfma_f32_16x16x32_bf16 v[56:59], v[160:163], v[184:187], v[56:59]
	v_mfma_f32_16x16x32_bf16 v[52:55], v[142:145], v[192:195], v[52:55]
	v_mfma_f32_16x16x32_bf16 v[48:51], v[160:163], v[192:195], v[48:51]
	v_mfma_f32_16x16x32_bf16 v[44:47], v[142:145], v[210:213], v[44:47]
	v_mfma_f32_16x16x32_bf16 v[40:43], v[160:163], v[210:213], v[40:43]
	v_mfma_f32_16x16x32_bf16 v[36:39], v[142:145], v[218:221], v[36:39]
	v_mfma_f32_16x16x32_bf16 v[32:35], v[160:163], v[218:221], v[32:35]
	v_mfma_f32_16x16x32_bf16 v[60:63], v[146:149], v[188:191], v[60:63]
	v_mfma_f32_16x16x32_bf16 v[56:59], v[164:167], v[188:191], v[56:59]
	v_mfma_f32_16x16x32_bf16 v[52:55], v[146:149], v[196:199], v[52:55]
	v_mfma_f32_16x16x32_bf16 v[48:51], v[164:167], v[196:199], v[48:51]
	v_mfma_f32_16x16x32_bf16 v[44:47], v[146:149], v[214:217], v[44:47]
	v_mfma_f32_16x16x32_bf16 v[40:43], v[164:167], v[214:217], v[40:43]
	v_mfma_f32_16x16x32_bf16 v[36:39], v[146:149], v[222:225], v[36:39]
	v_mfma_f32_16x16x32_bf16 v[32:35], v[164:167], v[222:225], v[32:35]
	s_setprio 0
	s_setprio 1
	v_mfma_f32_16x16x32_bf16 v[28:31], v[168:171], v[184:187], v[28:31]
	v_mfma_f32_16x16x32_bf16 v[24:27], v[176:179], v[184:187], v[24:27]
	v_mfma_f32_16x16x32_bf16 v[20:23], v[168:171], v[192:195], v[20:23]
	v_mfma_f32_16x16x32_bf16 v[16:19], v[176:179], v[192:195], v[16:19]
	v_mfma_f32_16x16x32_bf16 v[12:15], v[168:171], v[210:213], v[12:15]
	v_mfma_f32_16x16x32_bf16 v[8:11], v[176:179], v[210:213], v[8:11]
	v_mfma_f32_16x16x32_bf16 v[4:7], v[168:171], v[218:221], v[4:7]
	v_mfma_f32_16x16x32_bf16 v[0:3], v[176:179], v[218:221], v[0:3]
	v_mfma_f32_16x16x32_bf16 v[28:31], v[172:175], v[188:191], v[28:31]
	v_mfma_f32_16x16x32_bf16 v[24:27], v[180:183], v[188:191], v[24:27]
	v_mfma_f32_16x16x32_bf16 v[20:23], v[172:175], v[196:199], v[20:23]
	v_mfma_f32_16x16x32_bf16 v[16:19], v[180:183], v[196:199], v[16:19]
	v_mfma_f32_16x16x32_bf16 v[12:15], v[172:175], v[214:217], v[12:15]
	v_mfma_f32_16x16x32_bf16 v[8:11], v[180:183], v[214:217], v[8:11]
	v_mfma_f32_16x16x32_bf16 v[4:7], v[172:175], v[222:225], v[4:7]
	v_mfma_f32_16x16x32_bf16 v[0:3], v[180:183], v[222:225], v[0:3]
	s_setprio 0
	s_barrier
	s_add_i32 s28, s28, 2
	s_add_u32 s0, s0, 0x100
	s_addc_u32 s1, s1, 0
	s_cmp_gt_u32 s28, 29
	s_cbranch_scc0 .LBB0_362
.Lpeel_exit_362:
	s_and_b64 vcc, exec, s[6:7]
	s_cbranch_vccz .LBB0_365
	s_barrier
